# baseline (speedup 1.0000x reference)
; DEVINL void phase_conv(const Params& p, int layer, int wv) {
;     ...
;     for (int run = blockIdx.x * 2 + half; run < T_TOK / 32; run += gridDim.x * 2) {
;       const int tokA = run * 32;
;       const int l0 = tokA & 4095;
;       const u16* src = hb + (size_t)tokA * HS + 1024 + ch0;
;       bf16x8 r0, r1, r2;
;       const bf16x8 zero8 = {0, 0, 0, 0, 0, 0, 0, 0};
;       r0 = (l0 >= 3) ? *(const bf16x8*)(src - 3 * (long)HS) : zero8;
;       r1 = (l0 >= 2) ? *(const bf16x8*)(src - 2 * (long)HS) : zero8;
;       r2 = (l0 >= 1) ? *(const bf16x8*)(src - 1 * (long)HS) : zero8;
.LBB0_447:
	v_lshlrev_b32_e32 v41, 5, v88
	v_mov_b64_e32 v[42:43], s[94:95]
	v_mad_i64_i32 v[42:43], s[0:1], v41, s24, v[42:43]
	v_lshl_add_u64 v[42:43], v[56:57], 1, v[42:43]
	v_lshl_add_u64 v[62:63], v[42:43], 0, s[18:19]
	v_and_b32_e32 v41, 0x7f, v88
	v_mov_b32_e32 v42, v40
	v_mov_b32_e32 v43, v40
	v_cmp_ne_u32_e64 s[0:1], 0, v41
	v_mov_b32_e32 v41, v40
	v_mov_b64_e32 v[214:215], v[42:43]
	v_mov_b64_e32 v[212:213], v[40:41]
	s_and_saveexec_b64 s[2:3], s[0:1]
	s_cbranch_execz .LBB0_449
	v_add_co_u32_e32 v44, vcc, 0xffff9000, v62
	s_nop 1
	v_addc_co_u32_e32 v45, vcc, -1, v63, vcc
	global_load_dwordx4 v[212:215], v[44:45], off offset:-2048
.LBB0_449:
	s_or_b64 exec, exec, s[2:3]
	v_mov_b64_e32 v[218:219], v[42:43]
	v_mov_b64_e32 v[216:217], v[40:41]
	s_and_saveexec_b64 s[2:3], s[0:1]
	s_cbranch_execz .LBB0_451
	v_add_co_u32_e32 v42, vcc, 0xffffb000, v62
	s_nop 1
	v_addc_co_u32_e32 v43, vcc, -1, v63, vcc
	global_load_dwordx4 v[216:219], v[42:43], off
.LBB0_451:
	s_or_b64 exec, exec, s[2:3]
	v_mov_b32_e32 v42, v40
	v_mov_b32_e32 v43, v40
	v_mov_b32_e32 v41, v40
	v_mov_b64_e32 v[222:223], v[42:43]
	v_mov_b64_e32 v[220:221], v[40:41]
	s_and_saveexec_b64 s[2:3], s[0:1]
	s_cbranch_execz .LBB0_453
	v_add_co_u32_e32 v42, vcc, 0xffffe000, v62
	s_nop 1
	v_addc_co_u32_e32 v43, vcc, -1, v63, vcc
	global_load_dwordx4 v[220:223], v[42:43], off offset:-2048

; DEVINL u16 f2bf(float f) { uint32_t u = __float_as_uint(f); u += 0x7FFFu + ((u >> 16) & 1u); return (u16)(u >> 16); }
; DEVINL float bfs2f(short h) { return __uint_as_float(((uint32_t)(u16)h) << 16); }
; DEVINL void phase_conv(const Params& p, int layer, int wv) {
;     ...
; #pragma unroll 8
;       for (int i = 0; i < 32; ++i) {
;         const bf16x8 r3 = *(const bf16x8*)(src + (size_t)i * HS);
;         bf16x8 o;
; #pragma unroll
;         for (int e = 0; e < 8; ++e) {
;           float v = bias[e] + w[0][e] * bfs2f(r0[e]) + w[1][e] * bfs2f(r1[e]) + w[2][e] * bfs2f(r2[e]) + w[3][e] * bfs2f(r3[e]);
;           v = v / (1.f + __expf(-v));
;           o[e] = (short)f2bf(v);
;         }
;         *(bf16x8*)(xc + (size_t)(tokA + i) * 1536 + ch0) = o;
;         r0 = r1; r1 = r2; r2 = r3;
.LBB0_454:
	v_add_co_u32_e32 v62, vcc, 0xfffef000, v42
	s_waitcnt vmcnt(0)
	v_and_b32_e32 v75, 0xffff0000, v214
	v_addc_co_u32_e32 v63, vcc, -1, v43, vcc
	global_load_dwordx4 v[192:195], v[62:63], off offset:-2048
	v_lshlrev_b32_e32 v74, 16, v214
	v_add_co_u32_e64 v46, s[0:1], s31, v42
	v_and_b32_e32 v81, 0xffff0000, v215
	v_lshlrev_b32_e32 v80, 16, v215
	v_addc_co_u32_e64 v47, s[0:1], -1, v43, s[0:1]
	v_and_b32_e32 v69, 0xffff0000, v212
	v_lshlrev_b32_e32 v68, 16, v212
	v_and_b32_e32 v65, 0xffff0000, v220
	v_lshlrev_b32_e32 v64, 16, v220
	v_and_b32_e32 v73, 0xffff0000, v213
	v_lshlrev_b32_e32 v72, 16, v213
	v_and_b32_e32 v45, 0xffff0000, v221
	v_lshlrev_b32_e32 v44, 16, v221
	v_and_b32_e32 v53, 0xffff0000, v218
	v_lshlrev_b32_e32 v52, 16, v218
	v_add_co_u32_e64 v50, s[0:1], s33, v42
	v_and_b32_e32 v79, 0xffff0000, v219
	v_lshlrev_b32_e32 v78, 16, v219
	v_addc_co_u32_e64 v51, s[0:1], -1, v43, s[0:1]
	v_and_b32_e32 v67, 0xffff0000, v216
	v_lshlrev_b32_e32 v66, 16, v216
	v_and_b32_e32 v71, 0xffff0000, v217
	v_lshlrev_b32_e32 v70, 16, v217
	v_and_b32_e32 v49, 0xffff0000, v222
	v_lshlrev_b32_e32 v48, 16, v222
	v_add_co_u32_e64 v54, s[0:1], s34, v42
	v_and_b32_e32 v77, 0xffff0000, v223
	v_lshlrev_b32_e32 v76, 16, v223
	v_addc_co_u32_e64 v55, s[0:1], -1, v43, s[0:1]
	v_add_co_u32_e64 v82, s[0:1], s25, v42
	v_pk_fma_f32 v[68:69], v[4:5], v[68:69], v[36:37]
	s_nop 0
	v_addc_co_u32_e64 v83, s[0:1], -1, v43, s[0:1]
	v_add_co_u32_e64 v84, s[0:1], s26, v42
	v_pk_fma_f32 v[80:81], v[2:3], v[80:81], v[34:35]
	s_nop 0
	v_addc_co_u32_e64 v85, s[0:1], -1, v43, s[0:1]
	v_pk_fma_f32 v[96:97], v[4:5], v[66:67], v[36:37]
	v_pk_fma_f32 v[98:99], v[6:7], v[70:71], v[38:39]
	v_pk_fma_f32 v[100:101], v[0:1], v[52:53], v[32:33]
	v_pk_fma_f32 v[102:103], v[2:3], v[78:79], v[34:35]
	v_pk_fma_f32 v[112:113], v[8:9], v[66:67], v[68:69]
	v_pk_fma_f32 v[78:79], v[18:19], v[78:79], v[80:81]
	v_add_u32_e32 v41, s36, v89
	v_add_co_u32_e64 v86, s[0:1], s27, v42
	v_pk_fma_f32 v[72:73], v[6:7], v[72:73], v[38:39]
	v_pk_fma_f32 v[104:105], v[4:5], v[64:65], v[36:37]
	v_pk_fma_f32 v[110:111], v[2:3], v[76:77], v[34:35]
	v_pk_fma_f32 v[80:81], v[8:9], v[64:65], v[96:97]
	v_pk_fma_f32 v[96:97], v[10:11], v[44:45], v[98:99]
	v_pk_fma_f32 v[98:99], v[16:17], v[48:49], v[100:101]
	v_pk_fma_f32 v[100:101], v[18:19], v[76:77], v[102:103]
	v_pk_fma_f32 v[64:65], v[12:13], v[64:65], v[112:113]
	v_pk_fma_f32 v[76:77], v[22:23], v[76:77], v[78:79]
	v_addc_co_u32_e64 v87, s[0:1], -1, v43, s[0:1]
	global_load_dwordx4 v[196:199], v[46:47], off
	global_load_dwordx4 v[200:203], v[50:51], off offset:-2048
	global_load_dwordx4 v[204:207], v[54:55], off
	global_load_dwordx4 v[208:211], v[82:83], off offset:-2048
	global_load_dwordx4 v[212:215], v[84:85], off
	global_load_dwordx4 v[216:219], v[86:87], off offset:-2048
	global_load_dwordx4 v[220:223], v[42:43], off
	v_mad_i64_i32 v[94:95], s[0:1], v41, s30, v[58:59]
	v_add_u32_e32 v118, 1, v41
	v_add_u32_e32 v119, 2, v41
	v_add_u32_e32 v120, 3, v41
	v_add_u32_e32 v121, 4, v41
	v_add_u32_e32 v122, 5, v41
	v_add_u32_e32 v123, 6, v41
	v_add_u32_e32 v41, 7, v41
	v_pk_fma_f32 v[114:115], v[10:11], v[70:71], v[72:73]
	v_pk_fma_f32 v[74:75], v[0:1], v[74:75], v[32:33]
	v_pk_fma_f32 v[106:107], v[6:7], v[44:45], v[38:39]
	v_mad_i64_i32 v[62:63], s[0:1], v41, s30, v[58:59]
	s_waitcnt vmcnt(0)
	v_and_b32_e32 v79, 0xffff0000, v192
	v_lshlrev_b32_e32 v78, 16, v192
	v_and_b32_e32 v113, 0xffff0000, v195
	v_lshlrev_b32_e32 v112, 16, v195
	v_pk_fma_f32 v[64:65], v[24:25], v[78:79], v[64:65]
	v_pk_fma_f32 v[44:45], v[14:15], v[44:45], v[114:115]
	v_and_b32_e32 v103, 0xffff0000, v193
	v_lshlrev_b32_e32 v102, 16, v193
	v_and_b32_e32 v91, 0xffff0000, v194
	v_lshlrev_b32_e32 v90, 16, v194
	v_pk_fma_f32 v[92:93], v[30:31], v[112:113], v[76:77]
	v_mul_f32_e32 v41, 0xbfb8aa3b, v64
	v_mul_f32_e32 v77, 0xbfb8aa3b, v65
	v_pk_fma_f32 v[116:117], v[16:17], v[52:53], v[74:75]
	v_pk_fma_f32 v[44:45], v[26:27], v[102:103], v[44:45]
	v_exp_f32_e32 v76, v41
	v_exp_f32_e32 v77, v77
	v_pk_fma_f32 v[108:109], v[0:1], v[48:49], v[32:33]
	v_pk_fma_f32 v[48:49], v[20:21], v[48:49], v[116:117]
	v_pk_fma_f32 v[80:81], v[12:13], v[78:79], v[80:81]
	v_pk_fma_f32 v[104:105], v[8:9], v[78:79], v[104:105]
	v_pk_fma_f32 v[114:115], v[4:5], v[78:79], v[36:37]
	v_mul_f32_e32 v78, 0xbfb8aa3b, v44
	v_mul_f32_e32 v79, 0xbfb8aa3b, v45
	v_pk_fma_f32 v[48:49], v[28:29], v[90:91], v[48:49]
	v_exp_f32_e32 v78, v78
	v_exp_f32_e32 v79, v79
	v_mul_f32_e32 v116, 0xbfb8aa3b, v48
	v_mul_f32_e32 v117, 0xbfb8aa3b, v49
	v_exp_f32_e32 v116, v116
	v_exp_f32_e32 v117, v117
	v_pk_add_f32 v[76:77], v[76:77], 1.0 op_sel_hi:[1,0]
	v_mad_i64_i32 v[74:75], s[0:1], v118, s30, v[58:59]
	v_mad_i64_i32 v[72:73], s[0:1], v119, s30, v[58:59]
	v_mul_f32_e32 v118, 0xbfb8aa3b, v92
	v_mul_f32_e32 v119, 0xbfb8aa3b, v93
	v_mad_i64_i32 v[68:69], s[0:1], v121, s30, v[58:59]
	v_exp_f32_e32 v118, v118
	v_exp_f32_e32 v119, v119
	v_pk_add_f32 v[78:79], v[78:79], 1.0 op_sel_hi:[1,0]
	v_rcp_f32_e32 v135, v76
	v_mad_i64_i32 v[52:53], s[0:1], v123, s30, v[58:59]
	v_rcp_f32_e32 v136, v77
	v_pk_add_f32 v[116:117], v[116:117], 1.0 op_sel_hi:[1,0]
	v_rcp_f32_e32 v137, v78
	v_rcp_f32_e32 v138, v79
	v_pk_add_f32 v[118:119], v[118:119], 1.0 op_sel_hi:[1,0]
	v_rcp_f32_e32 v139, v116
	v_mad_i64_i32 v[70:71], s[0:1], v120, s30, v[58:59]
	v_mad_i64_i32 v[66:67], s[0:1], v122, s30, v[58:59]
	v_rcp_f32_e32 v140, v117
	v_rcp_f32_e32 v141, v118
	v_rcp_f32_e32 v142, v119
	v_mul_f32_e32 v41, v64, v135
	s_mov_b64 vcc, s[0:1]
	v_mul_f32_e32 v64, v65, v136
	s_mov_b64 vcc, s[2:3]
	v_mul_f32_e32 v65, v44, v137
	s_mov_b64 vcc, s[4:5]
	v_mov_b32_e32 v44, v65
; DEVINL u16 f2bf(float f) { uint32_t u = __float_as_uint(f); u += 0x7FFFu + ((u >> 16) & 1u); return (u16)(u >> 16); }
; DEVINL float bfs2f(short h) { return __uint_as_float(((uint32_t)(u16)h) << 16); }
; DEVINL void phase_conv(const Params& p, int layer, int wv) {
;     ...
; #pragma unroll 8
;       for (int i = 0; i < 32; ++i) {
;         const bf16x8 r3 = *(const bf16x8*)(src + (size_t)i * HS);
;         bf16x8 o;
; #pragma unroll
;         for (int e = 0; e < 8; ++e) {
;           float v = bias[e] + w[0][e] * bfs2f(r0[e]) + w[1][e] * bfs2f(r1[e]) + w[2][e] * bfs2f(r2[e]) + w[3][e] * bfs2f(r3[e]);
;           v = v / (1.f + __expf(-v));
;           o[e] = (short)f2bf(v);
;         }
;         *(bf16x8*)(xc + (size_t)(tokA + i) * 1536 + ch0) = o;
;         r0 = r1; r1 = r2; r2 = r3;
	v_mul_f32_e32 v65, v45, v138
	s_mov_b64 vcc, s[6:7]
	v_bfe_u32 v76, v41, 16, 1
	v_bfe_u32 v77, v64, 16, 1
	v_mov_b32_e32 v45, v65
	v_mul_f32_e32 v65, v48, v139
	s_mov_b64 vcc, s[8:9]
	v_add3_u32 v41, v41, v76, s28
	v_bfe_u32 v76, v44, 16, 1
	v_add3_u32 v64, v64, v77, s28
	v_mov_b32_e32 v48, v65
	v_mul_f32_e32 v65, v49, v140
	s_mov_b64 vcc, s[10:11]
	v_bfe_u32 v77, v45, 16, 1
	v_add3_u32 v44, v44, v76, s28
	v_perm_b32 v76, v64, v41, s29
	v_mov_b32_e32 v41, v65
	v_mul_f32_e32 v49, v92, v141
	s_mov_b64 vcc, s[12:13]
	v_add3_u32 v45, v45, v77, s28
	v_mul_f32_e32 v65, v93, v142
	v_bfe_u32 v64, v48, 16, 1
	v_bfe_u32 v78, v41, 16, 1
	v_perm_b32 v77, v45, v44, s29
	v_mov_b32_e32 v44, v65
	v_add3_u32 v48, v48, v64, s28
	v_bfe_u32 v45, v49, 16, 1
	v_add3_u32 v41, v41, v78, s28
	v_bfe_u32 v64, v44, 16, 1
	v_add3_u32 v45, v49, v45, s28
	v_perm_b32 v78, v41, v48, s29
	v_add3_u32 v41, v44, v64, s28
	v_perm_b32 v79, v41, v45, s29
	global_store_dwordx4 v[94:95], v[76:79], off
	v_pk_fma_f32 v[98:99], v[20:21], v[90:91], v[98:99]
	v_pk_fma_f32 v[108:109], v[16:17], v[90:91], v[108:109]
	v_pk_fma_f32 v[90:91], v[0:1], v[90:91], v[32:33]
	v_pk_fma_f32 v[96:97], v[14:15], v[102:103], v[96:97]
	v_pk_fma_f32 v[100:101], v[22:23], v[112:113], v[100:101]
	v_pk_fma_f32 v[110:111], v[18:19], v[112:113], v[110:111]
	v_pk_fma_f32 v[106:107], v[10:11], v[102:103], v[106:107]
	v_pk_fma_f32 v[112:113], v[2:3], v[112:113], v[34:35]
	v_pk_fma_f32 v[102:103], v[6:7], v[102:103], v[38:39]
	s_add_i32 s36, s36, 8
	s_cmp_eq_u32 s36, 32
	s_waitcnt vmcnt(0)
	v_and_b32_e32 v49, 0xffff0000, v196
	v_lshlrev_b32_e32 v48, 16, v196
	v_and_b32_e32 v65, 0xffff0000, v197
	v_lshlrev_b32_e32 v64, 16, v197
	v_and_b32_e32 v45, 0xffff0000, v198
	v_lshlrev_b32_e32 v44, 16, v198
	v_and_b32_e32 v77, 0xffff0000, v199
	v_lshlrev_b32_e32 v76, 16, v199
	v_pk_fma_f32 v[46:47], v[24:25], v[48:49], v[80:81]
	v_pk_fma_f32 v[80:81], v[28:29], v[44:45], v[98:99]
	v_pk_fma_f32 v[98:99], v[20:21], v[44:45], v[108:109]
	v_pk_fma_f32 v[90:91], v[16:17], v[44:45], v[90:91]
	v_pk_fma_f32 v[108:109], v[0:1], v[44:45], v[32:33]
	v_mul_f32_e32 v41, 0xbfb8aa3b, v46
	v_mul_f32_e32 v45, 0xbfb8aa3b, v47
	v_pk_fma_f32 v[78:79], v[26:27], v[64:65], v[96:97]
	v_exp_f32_e32 v44, v41
	v_exp_f32_e32 v45, v45
	v_pk_fma_f32 v[92:93], v[30:31], v[76:77], v[100:101]
	v_pk_fma_f32 v[100:101], v[22:23], v[76:77], v[110:111]
	v_mul_f32_e32 v110, 0xbfb8aa3b, v78
	v_mul_f32_e32 v111, 0xbfb8aa3b, v79
	v_exp_f32_e32 v110, v110
	v_exp_f32_e32 v111, v111
	v_pk_fma_f32 v[96:97], v[14:15], v[64:65], v[106:107]
	v_pk_fma_f32 v[106:107], v[18:19], v[76:77], v[112:113]
	v_mul_f32_e32 v112, 0xbfb8aa3b, v80
	v_mul_f32_e32 v113, 0xbfb8aa3b, v81
	v_exp_f32_e32 v112, v112
	v_exp_f32_e32 v113, v113
	v_pk_add_f32 v[44:45], v[44:45], 1.0 op_sel_hi:[1,0]
	v_pk_fma_f32 v[94:95], v[12:13], v[48:49], v[104:105]
	v_pk_fma_f32 v[104:105], v[8:9], v[48:49], v[114:115]
	v_mul_f32_e32 v114, 0xbfb8aa3b, v92
	v_mul_f32_e32 v115, 0xbfb8aa3b, v93
	v_exp_f32_e32 v114, v114
	v_exp_f32_e32 v115, v115
	v_pk_add_f32 v[110:111], v[110:111], 1.0 op_sel_hi:[1,0]
	v_rcp_f32_e32 v131, v44
	v_rcp_f32_e32 v132, v45
	v_pk_add_f32 v[112:113], v[112:113], 1.0 op_sel_hi:[1,0]
	v_rcp_f32_e32 v133, v110
	v_rcp_f32_e32 v134, v111
	v_pk_add_f32 v[114:115], v[114:115], 1.0 op_sel_hi:[1,0]
	v_rcp_f32_e32 v135, v112
	v_rcp_f32_e32 v136, v113
	v_rcp_f32_e32 v137, v114
	v_rcp_f32_e32 v138, v115
	v_mul_f32_e32 v41, v46, v131
	s_mov_b64 vcc, s[0:1]
	v_mul_f32_e32 v44, v47, v132
	s_mov_b64 vcc, s[2:3]
	v_mul_f32_e32 v45, v78, v133
	s_mov_b64 vcc, s[4:5]
	v_bfe_u32 v46, v41, 16, 1
	v_mul_f32_e32 v47, v79, v134
	s_mov_b64 vcc, s[6:7]
	v_bfe_u32 v78, v44, 16, 1
	v_add3_u32 v41, v41, v46, s28
	v_mov_b32_e32 v46, v47
	v_mul_f32_e32 v47, v80, v135
	s_mov_b64 vcc, s[8:9]
	v_add3_u32 v44, v44, v78, s28
	v_mul_f32_e32 v78, v81, v136
	s_mov_b64 vcc, s[10:11]
	v_bfe_u32 v79, v45, 16, 1
	v_bfe_u32 v80, v46, 16, 1
	v_perm_b32 v44, v44, v41, s29
	v_mov_b32_e32 v41, v78
	v_mul_f32_e32 v78, v92, v137
	s_mov_b64 vcc, s[12:13]
	v_add3_u32 v45, v45, v79, s28
	v_bfe_u32 v79, v47, 16, 1
	v_add3_u32 v46, v46, v80, s28
	v_mul_f32_e32 v80, v93, v138
	v_bfe_u32 v81, v41, 16, 1
	v_add3_u32 v47, v47, v79, s28
	v_mov_b32_e32 v79, v80
	v_perm_b32 v45, v46, v45, s29
	v_bfe_u32 v46, v78, 16, 1
	v_add3_u32 v41, v41, v81, s28
	v_bfe_u32 v80, v79, 16, 1
	v_add3_u32 v78, v78, v46, s28
	v_perm_b32 v46, v41, v47, s29
	v_add3_u32 v41, v79, v80, s28
	v_perm_b32 v47, v41, v78, s29
	global_store_dwordx4 v[74:75], v[44:47], off
	v_pk_fma_f32 v[102:103], v[10:11], v[64:65], v[102:103]
	v_pk_fma_f32 v[48:49], v[4:5], v[48:49], v[36:37]
	v_pk_fma_f32 v[64:65], v[6:7], v[64:65], v[38:39]
	v_pk_fma_f32 v[76:77], v[2:3], v[76:77], v[34:35]
	s_waitcnt vmcnt(0)
; DEVINL u16 f2bf(float f) { uint32_t u = __float_as_uint(f); u += 0x7FFFu + ((u >> 16) & 1u); return (u16)(u >> 16); }
; DEVINL float bfs2f(short h) { return __uint_as_float(((uint32_t)(u16)h) << 16); }
; DEVINL void phase_conv(const Params& p, int layer, int wv) {
;     ...
; #pragma unroll 8
;       for (int i = 0; i < 32; ++i) {
;         const bf16x8 r3 = *(const bf16x8*)(src + (size_t)i * HS);
;         bf16x8 o;
; #pragma unroll
;         for (int e = 0; e < 8; ++e) {
;           float v = bias[e] + w[0][e] * bfs2f(r0[e]) + w[1][e] * bfs2f(r1[e]) + w[2][e] * bfs2f(r2[e]) + w[3][e] * bfs2f(r3[e]);
;           v = v / (1.f + __expf(-v));
;           o[e] = (short)f2bf(v);
;         }
;         *(bf16x8*)(xc + (size_t)(tokA + i) * 1536 + ch0) = o;
;         r0 = r1; r1 = r2; r2 = r3;
	v_and_b32_e32 v51, 0xffff0000, v200
	v_lshlrev_b32_e32 v50, 16, v200
	v_and_b32_e32 v75, 0xffff0000, v201
	v_lshlrev_b32_e32 v74, 16, v201
	v_and_b32_e32 v45, 0xffff0000, v202
	v_lshlrev_b32_e32 v44, 16, v202
	v_and_b32_e32 v79, 0xffff0000, v203
	v_lshlrev_b32_e32 v78, 16, v203
	v_pk_fma_f32 v[46:47], v[24:25], v[50:51], v[94:95]
	v_pk_fma_f32 v[80:81], v[26:27], v[74:75], v[96:97]
	v_pk_fma_f32 v[92:93], v[28:29], v[44:45], v[98:99]
	v_pk_fma_f32 v[96:97], v[12:13], v[50:51], v[104:105]
	v_pk_fma_f32 v[98:99], v[14:15], v[74:75], v[102:103]
	v_pk_fma_f32 v[90:91], v[20:21], v[44:45], v[90:91]
	v_pk_fma_f32 v[102:103], v[16:17], v[44:45], v[108:109]
	v_pk_fma_f32 v[104:105], v[0:1], v[44:45], v[32:33]
	v_mul_f32_e32 v41, 0xbfb8aa3b, v46
	v_mul_f32_e32 v45, 0xbfb8aa3b, v47
	v_exp_f32_e32 v44, v41
	v_exp_f32_e32 v45, v45
	v_pk_fma_f32 v[94:95], v[30:31], v[78:79], v[100:101]
	v_pk_fma_f32 v[100:101], v[22:23], v[78:79], v[106:107]
	v_mul_f32_e32 v106, 0xbfb8aa3b, v80
	v_mul_f32_e32 v107, 0xbfb8aa3b, v81
	v_exp_f32_e32 v106, v106
	v_exp_f32_e32 v107, v107
	v_mul_f32_e32 v108, 0xbfb8aa3b, v92
	v_mul_f32_e32 v109, 0xbfb8aa3b, v93
	v_exp_f32_e32 v108, v108
	v_exp_f32_e32 v109, v109
	v_pk_add_f32 v[44:45], v[44:45], 1.0 op_sel_hi:[1,0]
	v_mul_f32_e32 v110, 0xbfb8aa3b, v94
	v_mul_f32_e32 v111, 0xbfb8aa3b, v95
	v_exp_f32_e32 v110, v110
	v_exp_f32_e32 v111, v111
	v_pk_add_f32 v[106:107], v[106:107], 1.0 op_sel_hi:[1,0]
	v_rcp_f32_e32 v127, v44
	v_rcp_f32_e32 v128, v45
	v_pk_add_f32 v[108:109], v[108:109], 1.0 op_sel_hi:[1,0]
	v_rcp_f32_e32 v129, v106
	v_rcp_f32_e32 v130, v107
	v_pk_add_f32 v[110:111], v[110:111], 1.0 op_sel_hi:[1,0]
	v_rcp_f32_e32 v131, v108
	v_rcp_f32_e32 v132, v109
	v_rcp_f32_e32 v133, v110
	v_rcp_f32_e32 v134, v111
	v_mul_f32_e32 v41, v46, v127
	s_mov_b64 vcc, s[0:1]
	v_mul_f32_e32 v44, v47, v128
	s_mov_b64 vcc, s[2:3]
	v_mul_f32_e32 v45, v80, v129
	s_mov_b64 vcc, s[4:5]
	v_bfe_u32 v46, v41, 16, 1
	v_mul_f32_e32 v47, v81, v130
	s_mov_b64 vcc, s[6:7]
	v_bfe_u32 v80, v44, 16, 1
	v_add3_u32 v41, v41, v46, s28
	v_mov_b32_e32 v46, v47
	v_mul_f32_e32 v47, v92, v131
	s_mov_b64 vcc, s[8:9]
	v_add3_u32 v44, v44, v80, s28
	v_mul_f32_e32 v80, v93, v132
	s_mov_b64 vcc, s[10:11]
	v_bfe_u32 v81, v45, 16, 1
	v_bfe_u32 v92, v46, 16, 1
	v_perm_b32 v44, v44, v41, s29
	v_mov_b32_e32 v41, v80
	v_mul_f32_e32 v80, v94, v133
	s_mov_b64 vcc, s[12:13]
	v_add3_u32 v45, v45, v81, s28
	v_bfe_u32 v81, v47, 16, 1
	v_add3_u32 v46, v46, v92, s28
	v_mul_f32_e32 v92, v95, v134
	v_bfe_u32 v93, v41, 16, 1
	v_add3_u32 v47, v47, v81, s28
	v_mov_b32_e32 v81, v92
	v_perm_b32 v45, v46, v45, s29
	v_bfe_u32 v46, v80, 16, 1
	v_add3_u32 v41, v41, v93, s28
	v_bfe_u32 v92, v81, 16, 1
	v_add3_u32 v80, v80, v46, s28
	v_perm_b32 v46, v41, v47, s29
	v_add3_u32 v41, v81, v92, s28
	v_perm_b32 v47, v41, v80, s29
	global_store_dwordx4 v[72:73], v[44:47], off
	v_pk_fma_f32 v[48:49], v[8:9], v[50:51], v[48:49]
	v_pk_fma_f32 v[64:65], v[10:11], v[74:75], v[64:65]
	v_pk_fma_f32 v[76:77], v[18:19], v[78:79], v[76:77]
	v_pk_fma_f32 v[50:51], v[4:5], v[50:51], v[36:37]
	v_pk_fma_f32 v[74:75], v[6:7], v[74:75], v[38:39]
	v_pk_fma_f32 v[78:79], v[2:3], v[78:79], v[34:35]
	s_waitcnt vmcnt(0)
	v_and_b32_e32 v55, 0xffff0000, v204
	v_lshlrev_b32_e32 v54, 16, v204
	v_and_b32_e32 v73, 0xffff0000, v205
	v_lshlrev_b32_e32 v72, 16, v205
	v_and_b32_e32 v45, 0xffff0000, v206
	v_lshlrev_b32_e32 v44, 16, v206
	v_and_b32_e32 v81, 0xffff0000, v207
	v_lshlrev_b32_e32 v80, 16, v207
	v_pk_fma_f32 v[46:47], v[24:25], v[54:55], v[96:97]
	v_pk_fma_f32 v[92:93], v[26:27], v[72:73], v[98:99]
	v_pk_fma_f32 v[90:91], v[28:29], v[44:45], v[90:91]
	v_pk_fma_f32 v[94:95], v[30:31], v[80:81], v[100:101]
	v_pk_fma_f32 v[96:97], v[20:21], v[44:45], v[102:103]
	v_pk_fma_f32 v[98:99], v[16:17], v[44:45], v[104:105]
	v_pk_fma_f32 v[100:101], v[0:1], v[44:45], v[32:33]
	v_mul_f32_e32 v41, 0xbfb8aa3b, v46
	v_mul_f32_e32 v45, 0xbfb8aa3b, v47
	v_exp_f32_e32 v44, v41
	v_exp_f32_e32 v45, v45
	v_mul_f32_e32 v102, 0xbfb8aa3b, v92
	v_mul_f32_e32 v103, 0xbfb8aa3b, v93
	v_exp_f32_e32 v102, v102
	v_exp_f32_e32 v103, v103
	v_mul_f32_e32 v104, 0xbfb8aa3b, v90
	v_mul_f32_e32 v105, 0xbfb8aa3b, v91
	v_exp_f32_e32 v104, v104
	v_exp_f32_e32 v105, v105
	v_pk_add_f32 v[44:45], v[44:45], 1.0 op_sel_hi:[1,0]
	v_mul_f32_e32 v106, 0xbfb8aa3b, v94
	v_mul_f32_e32 v107, 0xbfb8aa3b, v95
	v_exp_f32_e32 v106, v106
	v_exp_f32_e32 v107, v107
	v_pk_add_f32 v[102:103], v[102:103], 1.0 op_sel_hi:[1,0]
	v_rcp_f32_e32 v123, v44
	v_rcp_f32_e32 v124, v45
	v_pk_add_f32 v[104:105], v[104:105], 1.0 op_sel_hi:[1,0]
	v_rcp_f32_e32 v125, v102
	v_rcp_f32_e32 v126, v103
	v_pk_add_f32 v[106:107], v[106:107], 1.0 op_sel_hi:[1,0]
	v_rcp_f32_e32 v127, v104
	v_rcp_f32_e32 v128, v105
	v_rcp_f32_e32 v129, v106
	v_rcp_f32_e32 v130, v107
	v_mul_f32_e32 v41, v46, v123
	s_mov_b64 vcc, s[0:1]
	v_mul_f32_e32 v44, v47, v124
	s_mov_b64 vcc, s[2:3]
	v_mul_f32_e32 v45, v92, v125
	s_mov_b64 vcc, s[4:5]
	v_bfe_u32 v46, v41, 16, 1
	v_mul_f32_e32 v47, v93, v126
	s_mov_b64 vcc, s[6:7]
	v_bfe_u32 v92, v44, 16, 1
	v_add3_u32 v41, v41, v46, s28
	v_mov_b32_e32 v46, v47
	v_mul_f32_e32 v47, v90, v127
	s_mov_b64 vcc, s[8:9]
	v_add3_u32 v44, v44, v92, s28
	v_mul_f32_e32 v90, v91, v128
	s_mov_b64 vcc, s[10:11]
	v_bfe_u32 v92, v46, 16, 1
	v_perm_b32 v44, v44, v41, s29
	v_mov_b32_e32 v41, v90
	v_mul_f32_e32 v90, v94, v129
	s_mov_b64 vcc, s[12:13]
	v_bfe_u32 v93, v45, 16, 1
	v_bfe_u32 v91, v47, 16, 1
	v_add3_u32 v46, v46, v92, s28
	v_mul_f32_e32 v92, v95, v130
	v_add3_u32 v45, v45, v93, s28
	v_bfe_u32 v93, v41, 16, 1
	v_add3_u32 v47, v47, v91, s28
	v_mov_b32_e32 v91, v92
	v_perm_b32 v45, v46, v45, s29
	v_bfe_u32 v46, v90, 16, 1
	v_add3_u32 v41, v41, v93, s28
	v_bfe_u32 v92, v91, 16, 1
	v_add3_u32 v90, v90, v46, s28
	v_perm_b32 v46, v41, v47, s29
	v_add3_u32 v41, v91, v92, s28
	v_perm_b32 v47, v41, v90, s29
	global_store_dwordx4 v[70:71], v[44:47], off
	v_pk_fma_f32 v[48:49], v[12:13], v[54:55], v[48:49]
	v_pk_fma_f32 v[64:65], v[14:15], v[72:73], v[64:65]
	v_pk_fma_f32 v[76:77], v[22:23], v[80:81], v[76:77]
	v_pk_fma_f32 v[50:51], v[8:9], v[54:55], v[50:51]
	v_pk_fma_f32 v[54:55], v[4:5], v[54:55], v[36:37]
	v_pk_fma_f32 v[74:75], v[10:11], v[72:73], v[74:75]
	v_pk_fma_f32 v[72:73], v[6:7], v[72:73], v[38:39]
	v_pk_fma_f32 v[78:79], v[18:19], v[80:81], v[78:79]
	v_pk_fma_f32 v[80:81], v[2:3], v[80:81], v[34:35]
	s_waitcnt vmcnt(0)
; DEVINL u16 f2bf(float f) { uint32_t u = __float_as_uint(f); u += 0x7FFFu + ((u >> 16) & 1u); return (u16)(u >> 16); }
; DEVINL float bfs2f(short h) { return __uint_as_float(((uint32_t)(u16)h) << 16); }
; DEVINL void phase_conv(const Params& p, int layer, int wv) {
;     ...
; #pragma unroll 8
;       for (int i = 0; i < 32; ++i) {
;         const bf16x8 r3 = *(const bf16x8*)(src + (size_t)i * HS);
;         bf16x8 o;
; #pragma unroll
;         for (int e = 0; e < 8; ++e) {
;           float v = bias[e] + w[0][e] * bfs2f(r0[e]) + w[1][e] * bfs2f(r1[e]) + w[2][e] * bfs2f(r2[e]) + w[3][e] * bfs2f(r3[e]);
;           v = v / (1.f + __expf(-v));
;           o[e] = (short)f2bf(v);
;         }
;         *(bf16x8*)(xc + (size_t)(tokA + i) * 1536 + ch0) = o;
;         r0 = r1; r1 = r2; r2 = r3;
	v_and_b32_e32 v71, 0xffff0000, v208
	v_lshlrev_b32_e32 v70, 16, v208
	v_and_b32_e32 v83, 0xffff0000, v209
	v_lshlrev_b32_e32 v82, 16, v209
	v_and_b32_e32 v45, 0xffff0000, v210
	v_lshlrev_b32_e32 v44, 16, v210
	v_and_b32_e32 v91, 0xffff0000, v211
	v_lshlrev_b32_e32 v90, 16, v211
	v_pk_fma_f32 v[46:47], v[24:25], v[70:71], v[48:49]
	v_pk_fma_f32 v[48:49], v[26:27], v[82:83], v[64:65]
	v_pk_fma_f32 v[64:65], v[28:29], v[44:45], v[96:97]
	v_pk_fma_f32 v[92:93], v[20:21], v[44:45], v[98:99]
	v_pk_fma_f32 v[94:95], v[16:17], v[44:45], v[100:101]
	v_pk_fma_f32 v[96:97], v[0:1], v[44:45], v[32:33]
	v_mul_f32_e32 v41, 0xbfb8aa3b, v46
	v_mul_f32_e32 v45, 0xbfb8aa3b, v47
	v_exp_f32_e32 v44, v41
	v_exp_f32_e32 v45, v45
	v_mul_f32_e32 v98, 0xbfb8aa3b, v48
	v_mul_f32_e32 v99, 0xbfb8aa3b, v49
	v_exp_f32_e32 v98, v98
	v_exp_f32_e32 v99, v99
	v_mul_f32_e32 v100, 0xbfb8aa3b, v64
	v_mul_f32_e32 v101, 0xbfb8aa3b, v65
	v_pk_fma_f32 v[76:77], v[30:31], v[90:91], v[76:77]
	v_exp_f32_e32 v100, v100
	v_exp_f32_e32 v101, v101
	v_pk_add_f32 v[44:45], v[44:45], 1.0 op_sel_hi:[1,0]
	v_mul_f32_e32 v102, 0xbfb8aa3b, v76
	v_mul_f32_e32 v103, 0xbfb8aa3b, v77
	v_exp_f32_e32 v102, v102
	v_exp_f32_e32 v103, v103
	v_pk_add_f32 v[98:99], v[98:99], 1.0 op_sel_hi:[1,0]
	v_rcp_f32_e32 v119, v44
	v_rcp_f32_e32 v120, v45
	v_pk_add_f32 v[100:101], v[100:101], 1.0 op_sel_hi:[1,0]
	v_rcp_f32_e32 v121, v98
	v_rcp_f32_e32 v122, v99
	v_pk_add_f32 v[102:103], v[102:103], 1.0 op_sel_hi:[1,0]
	v_rcp_f32_e32 v123, v100
	v_rcp_f32_e32 v124, v101
	v_rcp_f32_e32 v125, v102
	v_rcp_f32_e32 v126, v103
	v_mul_f32_e32 v41, v46, v119
	s_mov_b64 vcc, s[0:1]
	v_mul_f32_e32 v44, v47, v120
	s_mov_b64 vcc, s[2:3]
	v_mul_f32_e32 v45, v48, v121
	s_mov_b64 vcc, s[4:5]
	v_bfe_u32 v46, v41, 16, 1
	v_mul_f32_e32 v47, v49, v122
	s_mov_b64 vcc, s[6:7]
	v_bfe_u32 v48, v44, 16, 1
	v_add3_u32 v41, v41, v46, s28
	v_mov_b32_e32 v46, v47
	v_mul_f32_e32 v47, v64, v123
	s_mov_b64 vcc, s[8:9]
	v_add3_u32 v44, v44, v48, s28
	v_mul_f32_e32 v48, v65, v124
	s_mov_b64 vcc, s[10:11]
	v_bfe_u32 v49, v45, 16, 1
	v_bfe_u32 v64, v46, 16, 1
	v_perm_b32 v44, v44, v41, s29
	v_mov_b32_e32 v41, v48
	v_mul_f32_e32 v48, v76, v125
	s_mov_b64 vcc, s[12:13]
	v_add3_u32 v45, v45, v49, s28
	v_bfe_u32 v49, v47, 16, 1
	v_add3_u32 v46, v46, v64, s28
	v_mul_f32_e32 v64, v77, v126
	v_bfe_u32 v65, v41, 16, 1
	v_add3_u32 v47, v47, v49, s28
	v_mov_b32_e32 v49, v64
	v_perm_b32 v45, v46, v45, s29
	v_bfe_u32 v46, v48, 16, 1
	v_add3_u32 v41, v41, v65, s28
	v_bfe_u32 v64, v49, 16, 1
	v_add3_u32 v48, v48, v46, s28
	v_perm_b32 v46, v41, v47, s29
	v_add3_u32 v41, v49, v64, s28
	v_perm_b32 v47, v41, v48, s29
	global_store_dwordx4 v[68:69], v[44:47], off
	v_pk_fma_f32 v[50:51], v[12:13], v[70:71], v[50:51]
	v_pk_fma_f32 v[54:55], v[8:9], v[70:71], v[54:55]
	v_pk_fma_f32 v[70:71], v[4:5], v[70:71], v[36:37]
	v_pk_fma_f32 v[74:75], v[14:15], v[82:83], v[74:75]
	v_pk_fma_f32 v[72:73], v[10:11], v[82:83], v[72:73]
	v_pk_fma_f32 v[82:83], v[6:7], v[82:83], v[38:39]
	v_pk_fma_f32 v[78:79], v[22:23], v[90:91], v[78:79]
	v_pk_fma_f32 v[80:81], v[18:19], v[90:91], v[80:81]
	v_pk_fma_f32 v[90:91], v[2:3], v[90:91], v[34:35]
	s_waitcnt vmcnt(0)
	v_and_b32_e32 v49, 0xffff0000, v212
	v_lshlrev_b32_e32 v48, 16, v212
	v_pk_fma_f32 v[50:51], v[24:25], v[48:49], v[50:51]
	v_and_b32_e32 v65, 0xffff0000, v213
	v_lshlrev_b32_e32 v64, 16, v213
	v_pk_fma_f32 v[54:55], v[12:13], v[48:49], v[54:55]
	v_pk_fma_f32 v[70:71], v[8:9], v[48:49], v[70:71]
	v_mul_f32_e32 v41, 0xbfb8aa3b, v50
	v_mul_f32_e32 v49, 0xbfb8aa3b, v51
	v_pk_fma_f32 v[74:75], v[26:27], v[64:65], v[74:75]
	v_exp_f32_e32 v48, v41
	v_exp_f32_e32 v49, v49
	v_and_b32_e32 v69, 0xffff0000, v214
	v_lshlrev_b32_e32 v68, 16, v214
	v_pk_fma_f32 v[72:73], v[14:15], v[64:65], v[72:73]
	v_pk_fma_f32 v[64:65], v[10:11], v[64:65], v[82:83]
	v_mul_f32_e32 v82, 0xbfb8aa3b, v74
	v_mul_f32_e32 v83, 0xbfb8aa3b, v75
	v_and_b32_e32 v77, 0xffff0000, v215
	v_lshlrev_b32_e32 v76, 16, v215
	v_pk_fma_f32 v[84:85], v[28:29], v[68:69], v[92:93]
	v_exp_f32_e32 v82, v82
	v_exp_f32_e32 v83, v83
	v_pk_fma_f32 v[78:79], v[30:31], v[76:77], v[78:79]
	v_pk_fma_f32 v[80:81], v[22:23], v[76:77], v[80:81]
	v_pk_fma_f32 v[76:77], v[18:19], v[76:77], v[90:91]
	v_mul_f32_e32 v90, 0xbfb8aa3b, v84
	v_mul_f32_e32 v91, 0xbfb8aa3b, v85
	v_exp_f32_e32 v90, v90
	v_exp_f32_e32 v91, v91
	v_pk_add_f32 v[48:49], v[48:49], 1.0 op_sel_hi:[1,0]
	v_pk_fma_f32 v[92:93], v[20:21], v[68:69], v[94:95]
	v_mul_f32_e32 v94, 0xbfb8aa3b, v78
	v_mul_f32_e32 v95, 0xbfb8aa3b, v79
	v_pk_fma_f32 v[68:69], v[16:17], v[68:69], v[96:97]
	v_exp_f32_e32 v94, v94
	v_exp_f32_e32 v95, v95
	v_pk_add_f32 v[82:83], v[82:83], 1.0 op_sel_hi:[1,0]
	v_rcp_f32_e32 v111, v48
	v_rcp_f32_e32 v112, v49
	v_pk_add_f32 v[90:91], v[90:91], 1.0 op_sel_hi:[1,0]
	v_rcp_f32_e32 v113, v82
	v_rcp_f32_e32 v114, v83
	v_pk_add_f32 v[94:95], v[94:95], 1.0 op_sel_hi:[1,0]
	v_rcp_f32_e32 v115, v90
	v_rcp_f32_e32 v116, v91
	v_rcp_f32_e32 v117, v94
	v_rcp_f32_e32 v118, v95
	v_mul_f32_e32 v41, v50, v111
	s_mov_b64 vcc, s[0:1]
	v_mul_f32_e32 v48, v51, v112
	s_mov_b64 vcc, s[2:3]
	v_mul_f32_e32 v49, v74, v113
	s_mov_b64 vcc, s[4:5]
	v_bfe_u32 v50, v41, 16, 1
	v_mul_f32_e32 v51, v75, v114
	s_mov_b64 vcc, s[6:7]
	v_bfe_u32 v74, v48, 16, 1
	v_add3_u32 v41, v41, v50, s28
	v_mov_b32_e32 v50, v51
	v_mul_f32_e32 v51, v84, v115
	s_mov_b64 vcc, s[8:9]
	v_add3_u32 v48, v48, v74, s28
	v_mul_f32_e32 v74, v85, v116
	s_mov_b64 vcc, s[10:11]
	v_bfe_u32 v75, v49, 16, 1
	v_perm_b32 v48, v48, v41, s29
	v_mov_b32_e32 v41, v74
	v_mul_f32_e32 v74, v78, v117
	s_mov_b64 vcc, s[12:13]
	v_bfe_u32 v82, v50, 16, 1
	v_add3_u32 v49, v49, v75, s28
	v_bfe_u32 v75, v51, 16, 1
	v_mul_f32_e32 v78, v79, v118
	v_add3_u32 v50, v50, v82, s28
	v_bfe_u32 v82, v41, 16, 1
	v_add3_u32 v51, v51, v75, s28
	v_mov_b32_e32 v75, v78
	v_perm_b32 v49, v50, v49, s29
	v_bfe_u32 v50, v74, 16, 1
	v_add3_u32 v41, v41, v82, s28
	v_bfe_u32 v78, v75, 16, 1
	v_add3_u32 v74, v74, v50, s28
	v_perm_b32 v50, v41, v51, s29
	v_add3_u32 v41, v75, v78, s28
	v_perm_b32 v51, v41, v74, s29
	global_store_dwordx4 v[66:67], v[48:51], off
	s_waitcnt vmcnt(0)
; DEVINL u16 f2bf(float f) { uint32_t u = __float_as_uint(f); u += 0x7FFFu + ((u >> 16) & 1u); return (u16)(u >> 16); }
; DEVINL float bfs2f(short h) { return __uint_as_float(((uint32_t)(u16)h) << 16); }
; DEVINL void phase_conv(const Params& p, int layer, int wv) {
;     ...
;     for (int run = blockIdx.x * 2 + half; run < T_TOK / 32; run += gridDim.x * 2) {
;     ...
; #pragma unroll 8
;       for (int i = 0; i < 32; ++i) {
;         const bf16x8 r3 = *(const bf16x8*)(src + (size_t)i * HS);
;         bf16x8 o;
; #pragma unroll
;         for (int e = 0; e < 8; ++e) {
;           float v = bias[e] + w[0][e] * bfs2f(r0[e]) + w[1][e] * bfs2f(r1[e]) + w[2][e] * bfs2f(r2[e]) + w[3][e] * bfs2f(r3[e]);
;           v = v / (1.f + __expf(-v));
;           o[e] = (short)f2bf(v);
;         }
;         *(bf16x8*)(xc + (size_t)(tokA + i) * 1536 + ch0) = o;
;         r0 = r1; r1 = r2; r2 = r3;
;       }
	v_and_b32_e32 v67, 0xffff0000, v216
	v_lshlrev_b32_e32 v66, 16, v216
	v_and_b32_e32 v75, 0xffff0000, v217
	v_lshlrev_b32_e32 v74, 16, v217
	v_pk_fma_f32 v[54:55], v[24:25], v[66:67], v[54:55]
	v_pk_fma_f32 v[72:73], v[26:27], v[74:75], v[72:73]
	v_pk_fma_f32 v[74:75], v[14:15], v[74:75], v[64:65]
	v_mul_f32_e32 v41, 0xbfb8aa3b, v54
	v_mul_f32_e32 v65, 0xbfb8aa3b, v55
	v_exp_f32_e32 v64, v41
	v_exp_f32_e32 v65, v65
	v_and_b32_e32 v79, 0xffff0000, v218
	v_lshlrev_b32_e32 v78, 16, v218
	v_pk_fma_f32 v[70:71], v[12:13], v[66:67], v[70:71]
	v_mul_f32_e32 v66, 0xbfb8aa3b, v72
	v_mul_f32_e32 v67, 0xbfb8aa3b, v73
	v_pk_fma_f32 v[84:85], v[28:29], v[78:79], v[92:93]
	v_exp_f32_e32 v66, v66
	v_exp_f32_e32 v67, v67
	v_and_b32_e32 v83, 0xffff0000, v219
	v_lshlrev_b32_e32 v82, 16, v219
	v_pk_fma_f32 v[68:69], v[20:21], v[78:79], v[68:69]
	v_mul_f32_e32 v78, 0xbfb8aa3b, v84
	v_mul_f32_e32 v79, 0xbfb8aa3b, v85
	v_pk_fma_f32 v[80:81], v[30:31], v[82:83], v[80:81]
	v_exp_f32_e32 v78, v78
	v_exp_f32_e32 v79, v79
	v_pk_add_f32 v[64:65], v[64:65], 1.0 op_sel_hi:[1,0]
	v_pk_fma_f32 v[76:77], v[22:23], v[82:83], v[76:77]
	v_mul_f32_e32 v82, 0xbfb8aa3b, v80
	v_mul_f32_e32 v83, 0xbfb8aa3b, v81
	v_exp_f32_e32 v82, v82
	v_exp_f32_e32 v83, v83
	v_pk_add_f32 v[66:67], v[66:67], 1.0 op_sel_hi:[1,0]
	v_rcp_f32_e32 v103, v64
	v_rcp_f32_e32 v104, v65
	v_pk_add_f32 v[78:79], v[78:79], 1.0 op_sel_hi:[1,0]
	v_rcp_f32_e32 v105, v66
	v_rcp_f32_e32 v106, v67
	v_pk_add_f32 v[82:83], v[82:83], 1.0 op_sel_hi:[1,0]
	v_rcp_f32_e32 v107, v78
	v_rcp_f32_e32 v108, v79
	v_rcp_f32_e32 v109, v82
	v_rcp_f32_e32 v110, v83
	v_mul_f32_e32 v41, v54, v103
	s_mov_b64 vcc, s[0:1]
	v_mul_f32_e32 v54, v55, v104
	s_mov_b64 vcc, s[2:3]
	v_mul_f32_e32 v55, v72, v105
	s_mov_b64 vcc, s[4:5]
	v_bfe_u32 v64, v41, 16, 1
	v_mul_f32_e32 v65, v73, v106
	s_mov_b64 vcc, s[6:7]
	v_bfe_u32 v66, v54, 16, 1
	v_add3_u32 v41, v41, v64, s28
	v_mul_f32_e32 v64, v84, v107
	s_mov_b64 vcc, s[8:9]
	v_add3_u32 v54, v54, v66, s28
	v_mul_f32_e32 v72, v85, v108
	s_mov_b64 vcc, s[10:11]
	v_bfe_u32 v67, v55, 16, 1
	v_mov_b32_e32 v66, v64
	v_bfe_u32 v73, v65, 16, 1
	v_perm_b32 v64, v54, v41, s29
	v_mul_f32_e32 v54, v80, v109
	s_mov_b64 vcc, s[12:13]
	v_add3_u32 v55, v55, v67, s28
	v_mov_b32_e32 v41, v72
	v_add3_u32 v65, v65, v73, s28
	v_mul_f32_e32 v72, v81, v110
	v_bfe_u32 v67, v66, 16, 1
	v_bfe_u32 v73, v41, 16, 1
	v_perm_b32 v65, v65, v55, s29
	v_mov_b32_e32 v55, v72
	v_add3_u32 v66, v66, v67, s28
	v_bfe_u32 v67, v54, 16, 1
	v_add3_u32 v41, v41, v73, s28
	v_bfe_u32 v72, v55, 16, 1
	v_add3_u32 v54, v54, v67, s28
	v_perm_b32 v66, v41, v66, s29
	v_add3_u32 v41, v55, v72, s28
	v_perm_b32 v67, v41, v54, s29
	global_store_dwordx4 v[52:53], v[64:67], off
	v_lshl_add_u64 v[42:43], v[42:43], 0, s[20:21]
	s_waitcnt vmcnt(0)
	v_and_b32_e32 v65, 0xffff0000, v220
	v_lshlrev_b32_e32 v64, 16, v220
	v_and_b32_e32 v73, 0xffff0000, v222
	v_lshlrev_b32_e32 v72, 16, v222
	v_pk_fma_f32 v[64:65], v[24:25], v[64:65], v[70:71]
	v_and_b32_e32 v67, 0xffff0000, v221
	v_lshlrev_b32_e32 v66, 16, v221
	v_pk_fma_f32 v[68:69], v[28:29], v[72:73], v[68:69]
	v_mul_f32_e32 v41, 0xbfb8aa3b, v64
	v_mul_f32_e32 v73, 0xbfb8aa3b, v65
	v_pk_fma_f32 v[66:67], v[26:27], v[66:67], v[74:75]
	v_exp_f32_e32 v72, v41
	v_exp_f32_e32 v73, v73
	v_mul_f32_e32 v74, 0xbfb8aa3b, v66
	v_mul_f32_e32 v75, 0xbfb8aa3b, v67
	v_and_b32_e32 v79, 0xffff0000, v223
	v_lshlrev_b32_e32 v78, 16, v223
	v_exp_f32_e32 v74, v74
	v_exp_f32_e32 v75, v75
	v_pk_fma_f32 v[70:71], v[30:31], v[78:79], v[76:77]
	v_mul_f32_e32 v76, 0xbfb8aa3b, v68
	v_mul_f32_e32 v77, 0xbfb8aa3b, v69
	v_exp_f32_e32 v76, v76
	v_exp_f32_e32 v77, v77
	v_pk_add_f32 v[72:73], v[72:73], 1.0 op_sel_hi:[1,0]
	v_mul_f32_e32 v78, 0xbfb8aa3b, v70
	v_mul_f32_e32 v79, 0xbfb8aa3b, v71
	v_exp_f32_e32 v78, v78
	v_exp_f32_e32 v79, v79
	v_pk_add_f32 v[74:75], v[74:75], 1.0 op_sel_hi:[1,0]
	v_rcp_f32_e32 v97, v72
	v_rcp_f32_e32 v98, v73
	v_pk_add_f32 v[76:77], v[76:77], 1.0 op_sel_hi:[1,0]
	v_rcp_f32_e32 v99, v74
	v_rcp_f32_e32 v100, v75
	v_pk_add_f32 v[78:79], v[78:79], 1.0 op_sel_hi:[1,0]
	v_rcp_f32_e32 v101, v76
	v_rcp_f32_e32 v102, v77
	v_rcp_f32_e32 v103, v78
	v_rcp_f32_e32 v104, v79
	v_mul_f32_e32 v41, v64, v97
	s_mov_b64 vcc, s[0:1]
	v_mul_f32_e32 v64, v65, v98
	s_mov_b64 vcc, s[2:3]
	v_mul_f32_e32 v65, v66, v99
	s_mov_b64 vcc, s[4:5]
	v_mul_f32_e32 v66, v67, v100
	s_mov_b64 vcc, s[6:7]
	v_bfe_u32 v72, v41, 16, 1
	v_bfe_u32 v73, v64, 16, 1
	v_mul_f32_e32 v67, v68, v101
	s_mov_b64 vcc, s[8:9]
	v_add3_u32 v41, v41, v72, s28
	v_add3_u32 v64, v64, v73, s28
	v_mul_f32_e32 v68, v69, v102
	s_mov_b64 vcc, s[10:11]
	v_perm_b32 v64, v64, v41, s29
	v_mov_b32_e32 v41, v68
	v_mul_f32_e32 v68, v70, v103
	s_mov_b64 vcc, s[12:13]
	v_bfe_u32 v72, v65, 16, 1
	v_bfe_u32 v73, v66, 16, 1
	v_bfe_u32 v69, v67, 16, 1
	v_mul_f32_e32 v70, v71, v104
	v_add3_u32 v65, v65, v72, s28
	v_add3_u32 v66, v66, v73, s28
	v_bfe_u32 v72, v41, 16, 1
	v_add3_u32 v67, v67, v69, s28
	v_mov_b32_e32 v69, v70
	v_perm_b32 v65, v66, v65, s29
	v_bfe_u32 v66, v68, 16, 1
	v_add3_u32 v41, v41, v72, s28
	v_bfe_u32 v70, v69, 16, 1
	v_add3_u32 v68, v68, v66, s28
	v_perm_b32 v66, v41, v67, s29
	v_add3_u32 v41, v69, v70, s28
	v_perm_b32 v67, v41, v68, s29
	global_store_dwordx4 v[62:63], v[64:67], off
	s_cbranch_scc0 .LBB0_454
	v_add_u32_e32 v88, s22, v88
	v_cmp_lt_i32_e32 vcc, s35, v88
	s_or_b64 s[16:17], vcc, s[16:17]
	v_add_u32_e32 v89, s23, v89
	s_andn2_b64 exec, exec, s[16:17]
	s_cbranch_execnz .LBB0_447

; DEVINL void phase_conv(const Params& p, int layer, int wv) {
;     ...
;     for (int run = blockIdx.x * 2 + half; run < T_TOK / 32; run += gridDim.x * 2) {
;       const int tokA = run * 32;
;       const int l0 = tokA & 4095;
;       const u16* src = hb + (size_t)tokA * HS + 1024 + ch0;
;       bf16x8 r0, r1, r2;
;       const bf16x8 zero8 = {0, 0, 0, 0, 0, 0, 0, 0};
;       r0 = (l0 >= 3) ? *(const bf16x8*)(src - 3 * (long)HS) : zero8;
;       r1 = (l0 >= 2) ? *(const bf16x8*)(src - 2 * (long)HS) : zero8;
;       r2 = (l0 >= 1) ? *(const bf16x8*)(src - 1 * (long)HS) : zero8;
.LBB0_1470:
	v_lshlrev_b32_e32 v41, 5, v88
	v_mov_b64_e32 v[42:43], s[94:95]
	v_mad_i64_i32 v[42:43], s[0:1], v41, s26, v[42:43]
	v_lshl_add_u64 v[42:43], v[56:57], 1, v[42:43]
	v_lshl_add_u64 v[62:63], v[42:43], 0, s[20:21]
	v_and_b32_e32 v41, 0x7f, v88
	v_mov_b32_e32 v42, v40
	v_mov_b32_e32 v43, v40
	v_cmp_ne_u32_e64 s[2:3], 0, v41
	v_mov_b32_e32 v41, v40
	s_waitcnt vmcnt(28)
	v_mov_b64_e32 v[214:215], v[42:43]
	v_mov_b64_e32 v[212:213], v[40:41]
	s_and_saveexec_b64 s[4:5], s[2:3]
	s_cbranch_execz .LBB0_1472
	v_add_co_u32_e32 v44, vcc, 0xffff9000, v62
	s_nop 1
	v_addc_co_u32_e32 v45, vcc, -1, v63, vcc
	global_load_dwordx4 v[212:215], v[44:45], off offset:-2048
.LBB0_1472:
	s_or_b64 exec, exec, s[4:5]
	s_waitcnt vmcnt(27)
	v_mov_b64_e32 v[218:219], v[42:43]
	v_mov_b64_e32 v[216:217], v[40:41]
	s_and_saveexec_b64 s[4:5], s[2:3]
	s_cbranch_execz .LBB0_1474
	v_add_co_u32_e32 v42, vcc, 0xffffb000, v62
	s_nop 1
	v_addc_co_u32_e32 v43, vcc, -1, v63, vcc
	global_load_dwordx4 v[216:219], v[42:43], off
.LBB0_1474:
	s_or_b64 exec, exec, s[4:5]
	v_mov_b32_e32 v42, v40
	v_mov_b32_e32 v43, v40
	v_mov_b32_e32 v41, v40
	v_mov_b64_e32 v[222:223], v[42:43]
	v_mov_b64_e32 v[220:221], v[40:41]
	s_and_saveexec_b64 s[4:5], s[2:3]
	s_cbranch_execz .LBB0_1476
	v_add_co_u32_e32 v42, vcc, 0xffffe000, v62
	s_nop 1
	v_addc_co_u32_e32 v43, vcc, -1, v63, vcc
	global_load_dwordx4 v[220:223], v[42:43], off offset:-2048

; DEVINL u16 f2bf(float f) { uint32_t u = __float_as_uint(f); u += 0x7FFFu + ((u >> 16) & 1u); return (u16)(u >> 16); }
; DEVINL float bfs2f(short h) { return __uint_as_float(((uint32_t)(u16)h) << 16); }
; DEVINL void phase_conv(const Params& p, int layer, int wv) {
;     ...
; #pragma unroll 8
;       for (int i = 0; i < 32; ++i) {
;         const bf16x8 r3 = *(const bf16x8*)(src + (size_t)i * HS);
;         bf16x8 o;
; #pragma unroll
;         for (int e = 0; e < 8; ++e) {
;           float v = bias[e] + w[0][e] * bfs2f(r0[e]) + w[1][e] * bfs2f(r1[e]) + w[2][e] * bfs2f(r2[e]) + w[3][e] * bfs2f(r3[e]);
;           v = v / (1.f + __expf(-v));
;           o[e] = (short)f2bf(v);
;         }
;         *(bf16x8*)(xc + (size_t)(tokA + i) * 1536 + ch0) = o;
;         r0 = r1; r1 = r2; r2 = r3;
.LBB0_1477:
	v_add_co_u32_e32 v62, vcc, 0xfffef000, v42
	s_waitcnt vmcnt(0)
	v_and_b32_e32 v69, 0xffff0000, v212
	v_addc_co_u32_e32 v63, vcc, -1, v43, vcc
	global_load_dwordx4 v[192:195], v[62:63], off offset:-2048
	v_lshlrev_b32_e32 v68, 16, v212
	v_and_b32_e32 v81, 0xffff0000, v215
	v_lshlrev_b32_e32 v80, 16, v215
	v_and_b32_e32 v67, 0xffff0000, v216
	v_lshlrev_b32_e32 v66, 16, v216
	v_and_b32_e32 v65, 0xffff0000, v220
	v_lshlrev_b32_e32 v64, 16, v220
	v_and_b32_e32 v73, 0xffff0000, v213
	v_lshlrev_b32_e32 v72, 16, v213
	v_and_b32_e32 v71, 0xffff0000, v217
	v_lshlrev_b32_e32 v70, 16, v217
	v_and_b32_e32 v45, 0xffff0000, v221
	v_lshlrev_b32_e32 v44, 16, v221
	v_and_b32_e32 v53, 0xffff0000, v218
	v_lshlrev_b32_e32 v52, 16, v218
	v_and_b32_e32 v79, 0xffff0000, v219
	v_lshlrev_b32_e32 v78, 16, v219
	v_pk_fma_f32 v[68:69], v[0:1], v[68:69], v[32:33]
	v_pk_fma_f32 v[80:81], v[10:11], v[80:81], v[38:39]
	v_and_b32_e32 v49, 0xffff0000, v222
	v_lshlrev_b32_e32 v48, 16, v222
	v_and_b32_e32 v77, 0xffff0000, v223
	v_lshlrev_b32_e32 v76, 16, v223
	v_pk_fma_f32 v[96:97], v[0:1], v[66:67], v[32:33]
	v_pk_fma_f32 v[98:99], v[2:3], v[70:71], v[34:35]
	v_pk_fma_f32 v[100:101], v[8:9], v[52:53], v[36:37]
	v_pk_fma_f32 v[102:103], v[10:11], v[78:79], v[38:39]
	v_pk_fma_f32 v[112:113], v[4:5], v[66:67], v[68:69]
	v_pk_fma_f32 v[78:79], v[14:15], v[78:79], v[80:81]
	v_add_u32_e32 v41, s38, v89
	v_pk_fma_f32 v[72:73], v[2:3], v[72:73], v[34:35]
	v_pk_fma_f32 v[104:105], v[0:1], v[64:65], v[32:33]
	v_pk_fma_f32 v[110:111], v[10:11], v[76:77], v[38:39]
	v_pk_fma_f32 v[80:81], v[4:5], v[64:65], v[96:97]
	v_pk_fma_f32 v[96:97], v[6:7], v[44:45], v[98:99]
	v_pk_fma_f32 v[98:99], v[12:13], v[48:49], v[100:101]
	v_pk_fma_f32 v[100:101], v[14:15], v[76:77], v[102:103]
	v_pk_fma_f32 v[64:65], v[16:17], v[64:65], v[112:113]
	v_pk_fma_f32 v[76:77], v[26:27], v[76:77], v[78:79]
	v_and_b32_e32 v75, 0xffff0000, v214
	v_lshlrev_b32_e32 v74, 16, v214
	v_mad_i64_i32 v[94:95], s[0:1], v41, s33, v[58:59]
	v_add_u32_e32 v118, 1, v41
	v_add_u32_e32 v119, 2, v41
	v_add_u32_e32 v120, 3, v41
	v_add_u32_e32 v121, 4, v41
	v_add_u32_e32 v122, 5, v41
	v_add_u32_e32 v123, 6, v41
	v_add_u32_e32 v41, 7, v41
	v_pk_fma_f32 v[114:115], v[6:7], v[70:71], v[72:73]
	v_pk_fma_f32 v[74:75], v[8:9], v[74:75], v[36:37]
	v_pk_fma_f32 v[106:107], v[2:3], v[44:45], v[34:35]
	v_mad_i64_i32 v[62:63], s[0:1], v41, s33, v[58:59]
	v_pk_fma_f32 v[44:45], v[18:19], v[44:45], v[114:115]
	v_add_co_u32_e64 v46, s[2:3], s34, v42
	v_pk_fma_f32 v[116:117], v[12:13], v[52:53], v[74:75]
	s_nop 0
	v_addc_co_u32_e64 v47, s[2:3], -1, v43, s[2:3]
	v_pk_fma_f32 v[108:109], v[8:9], v[48:49], v[36:37]
	v_pk_fma_f32 v[48:49], v[24:25], v[48:49], v[116:117]
	v_add_co_u32_e64 v50, s[2:3], s35, v42
	v_mad_i64_i32 v[74:75], s[0:1], v118, s33, v[58:59]
	s_nop 0
	v_addc_co_u32_e64 v51, s[2:3], -1, v43, s[2:3]
	v_add_co_u32_e64 v54, s[2:3], s36, v42
	v_mad_i64_i32 v[72:73], s[0:1], v119, s33, v[58:59]
	s_nop 0
	v_addc_co_u32_e64 v55, s[2:3], -1, v43, s[2:3]
	v_add_co_u32_e64 v82, s[2:3], s27, v42
	v_mad_i64_i32 v[68:69], s[0:1], v121, s33, v[58:59]
	s_waitcnt vmcnt(0)
	v_and_b32_e32 v79, 0xffff0000, v192
	v_lshlrev_b32_e32 v78, 16, v192
	v_and_b32_e32 v113, 0xffff0000, v195
	v_lshlrev_b32_e32 v112, 16, v195
	v_pk_fma_f32 v[64:65], v[20:21], v[78:79], v[64:65]
	v_and_b32_e32 v103, 0xffff0000, v193
	v_lshlrev_b32_e32 v102, 16, v193
	v_and_b32_e32 v91, 0xffff0000, v194
	v_lshlrev_b32_e32 v90, 16, v194
	v_pk_fma_f32 v[92:93], v[30:31], v[112:113], v[76:77]
	v_mul_f32_e32 v41, 0xbfb8aa3b, v64
	v_mul_f32_e32 v77, 0xbfb8aa3b, v65
	v_pk_fma_f32 v[44:45], v[22:23], v[102:103], v[44:45]
	v_exp_f32_e32 v76, v41
	v_exp_f32_e32 v77, v77
	v_pk_fma_f32 v[80:81], v[16:17], v[78:79], v[80:81]
	v_pk_fma_f32 v[104:105], v[4:5], v[78:79], v[104:105]
	v_pk_fma_f32 v[114:115], v[0:1], v[78:79], v[32:33]
	v_mul_f32_e32 v78, 0xbfb8aa3b, v44
	v_mul_f32_e32 v79, 0xbfb8aa3b, v45
	v_pk_fma_f32 v[48:49], v[28:29], v[90:91], v[48:49]
	v_exp_f32_e32 v78, v78
	v_exp_f32_e32 v79, v79
	v_mul_f32_e32 v116, 0xbfb8aa3b, v48
	v_mul_f32_e32 v117, 0xbfb8aa3b, v49
	v_exp_f32_e32 v116, v116
	v_exp_f32_e32 v117, v117
	v_pk_add_f32 v[76:77], v[76:77], 1.0 op_sel_hi:[1,0]
	v_mul_f32_e32 v118, 0xbfb8aa3b, v92
	v_mul_f32_e32 v119, 0xbfb8aa3b, v93
	v_exp_f32_e32 v118, v118
	v_exp_f32_e32 v119, v119
	v_pk_add_f32 v[78:79], v[78:79], 1.0 op_sel_hi:[1,0]
	v_rcp_f32_e32 v135, v76
	v_addc_co_u32_e64 v83, s[2:3], -1, v43, s[2:3]
	v_mad_i64_i32 v[52:53], s[0:1], v123, s33, v[58:59]
	v_rcp_f32_e32 v136, v77
	v_add_co_u32_e64 v84, s[2:3], s28, v42
	v_pk_add_f32 v[116:117], v[116:117], 1.0 op_sel_hi:[1,0]
	v_rcp_f32_e32 v137, v78
	v_addc_co_u32_e64 v85, s[2:3], -1, v43, s[2:3]
	v_rcp_f32_e32 v138, v79
	v_add_co_u32_e64 v86, s[2:3], s29, v42
	v_pk_add_f32 v[118:119], v[118:119], 1.0 op_sel_hi:[1,0]
	v_rcp_f32_e32 v139, v116
	v_addc_co_u32_e64 v87, s[2:3], -1, v43, s[2:3]
	global_load_dwordx4 v[196:199], v[46:47], off
	global_load_dwordx4 v[200:203], v[50:51], off offset:-2048
	global_load_dwordx4 v[204:207], v[54:55], off
	global_load_dwordx4 v[208:211], v[82:83], off offset:-2048
	global_load_dwordx4 v[212:215], v[84:85], off
	global_load_dwordx4 v[216:219], v[86:87], off offset:-2048
	global_load_dwordx4 v[220:223], v[42:43], off
	v_mad_i64_i32 v[70:71], s[0:1], v120, s33, v[58:59]
	v_rcp_f32_e32 v140, v117
	v_mad_i64_i32 v[66:67], s[0:1], v122, s33, v[58:59]
	v_rcp_f32_e32 v141, v118
	v_rcp_f32_e32 v142, v119
	v_mul_f32_e32 v41, v64, v135
	s_mov_b64 vcc, s[2:3]
	v_mul_f32_e32 v64, v65, v136
	s_mov_b64 vcc, s[4:5]
	v_mul_f32_e32 v65, v44, v137
	s_mov_b64 vcc, s[6:7]
	v_mov_b32_e32 v44, v65
; DEVINL u16 f2bf(float f) { uint32_t u = __float_as_uint(f); u += 0x7FFFu + ((u >> 16) & 1u); return (u16)(u >> 16); }
; DEVINL float bfs2f(short h) { return __uint_as_float(((uint32_t)(u16)h) << 16); }
; DEVINL void phase_conv(const Params& p, int layer, int wv) {
;     ...
; #pragma unroll 8
;       for (int i = 0; i < 32; ++i) {
;         const bf16x8 r3 = *(const bf16x8*)(src + (size_t)i * HS);
;         bf16x8 o;
; #pragma unroll
;         for (int e = 0; e < 8; ++e) {
;           float v = bias[e] + w[0][e] * bfs2f(r0[e]) + w[1][e] * bfs2f(r1[e]) + w[2][e] * bfs2f(r2[e]) + w[3][e] * bfs2f(r3[e]);
;           v = v / (1.f + __expf(-v));
;           o[e] = (short)f2bf(v);
;         }
;         *(bf16x8*)(xc + (size_t)(tokA + i) * 1536 + ch0) = o;
;         r0 = r1; r1 = r2; r2 = r3;
	v_mul_f32_e32 v65, v45, v138
	s_mov_b64 vcc, s[8:9]
	v_bfe_u32 v76, v41, 16, 1
	v_bfe_u32 v77, v64, 16, 1
	v_mov_b32_e32 v45, v65
	v_mul_f32_e32 v65, v48, v139
	s_mov_b64 vcc, s[10:11]
	v_add3_u32 v41, v41, v76, s30
	v_bfe_u32 v76, v44, 16, 1
	v_add3_u32 v64, v64, v77, s30
	v_mov_b32_e32 v48, v65
	v_mul_f32_e32 v65, v49, v140
	s_mov_b64 vcc, s[12:13]
	v_bfe_u32 v77, v45, 16, 1
	v_add3_u32 v44, v44, v76, s30
	v_perm_b32 v76, v64, v41, s31
	v_mov_b32_e32 v41, v65
	v_mul_f32_e32 v49, v92, v141
	s_mov_b64 vcc, s[14:15]
	v_add3_u32 v45, v45, v77, s30
	v_mul_f32_e32 v65, v93, v142
	v_bfe_u32 v64, v48, 16, 1
	v_bfe_u32 v78, v41, 16, 1
	v_perm_b32 v77, v45, v44, s31
	v_mov_b32_e32 v44, v65
	v_add3_u32 v48, v48, v64, s30
	v_bfe_u32 v45, v49, 16, 1
	v_add3_u32 v41, v41, v78, s30
	v_bfe_u32 v64, v44, 16, 1
	v_add3_u32 v45, v49, v45, s30
	v_perm_b32 v78, v41, v48, s31
	v_add3_u32 v41, v44, v64, s30
	v_perm_b32 v79, v41, v45, s31
	global_store_dwordx4 v[94:95], v[76:79], off
	v_pk_fma_f32 v[98:99], v[24:25], v[90:91], v[98:99]
	v_pk_fma_f32 v[108:109], v[12:13], v[90:91], v[108:109]
	v_pk_fma_f32 v[90:91], v[8:9], v[90:91], v[36:37]
	v_pk_fma_f32 v[96:97], v[18:19], v[102:103], v[96:97]
	v_pk_fma_f32 v[100:101], v[26:27], v[112:113], v[100:101]
	v_pk_fma_f32 v[110:111], v[14:15], v[112:113], v[110:111]
	v_pk_fma_f32 v[106:107], v[6:7], v[102:103], v[106:107]
	v_pk_fma_f32 v[112:113], v[10:11], v[112:113], v[38:39]
	v_pk_fma_f32 v[102:103], v[2:3], v[102:103], v[34:35]
	s_add_i32 s38, s38, 8
	s_cmp_eq_u32 s38, 32
	s_waitcnt vmcnt(0)
	v_and_b32_e32 v49, 0xffff0000, v196
	v_lshlrev_b32_e32 v48, 16, v196
	v_and_b32_e32 v65, 0xffff0000, v197
	v_lshlrev_b32_e32 v64, 16, v197
	v_and_b32_e32 v45, 0xffff0000, v198
	v_lshlrev_b32_e32 v44, 16, v198
	v_and_b32_e32 v77, 0xffff0000, v199
	v_lshlrev_b32_e32 v76, 16, v199
	v_pk_fma_f32 v[46:47], v[20:21], v[48:49], v[80:81]
	v_pk_fma_f32 v[80:81], v[28:29], v[44:45], v[98:99]
	v_pk_fma_f32 v[98:99], v[24:25], v[44:45], v[108:109]
	v_pk_fma_f32 v[90:91], v[12:13], v[44:45], v[90:91]
	v_pk_fma_f32 v[108:109], v[8:9], v[44:45], v[36:37]
	v_mul_f32_e32 v41, 0xbfb8aa3b, v46
	v_mul_f32_e32 v45, 0xbfb8aa3b, v47
	v_pk_fma_f32 v[78:79], v[22:23], v[64:65], v[96:97]
	v_exp_f32_e32 v44, v41
	v_exp_f32_e32 v45, v45
	v_pk_fma_f32 v[92:93], v[30:31], v[76:77], v[100:101]
	v_pk_fma_f32 v[100:101], v[26:27], v[76:77], v[110:111]
	v_mul_f32_e32 v110, 0xbfb8aa3b, v78
	v_mul_f32_e32 v111, 0xbfb8aa3b, v79
	v_exp_f32_e32 v110, v110
	v_exp_f32_e32 v111, v111
	v_pk_fma_f32 v[96:97], v[18:19], v[64:65], v[106:107]
	v_pk_fma_f32 v[106:107], v[14:15], v[76:77], v[112:113]
	v_mul_f32_e32 v112, 0xbfb8aa3b, v80
	v_mul_f32_e32 v113, 0xbfb8aa3b, v81
	v_exp_f32_e32 v112, v112
	v_exp_f32_e32 v113, v113
	v_pk_add_f32 v[44:45], v[44:45], 1.0 op_sel_hi:[1,0]
	v_pk_fma_f32 v[94:95], v[16:17], v[48:49], v[104:105]
	v_pk_fma_f32 v[104:105], v[4:5], v[48:49], v[114:115]
	v_mul_f32_e32 v114, 0xbfb8aa3b, v92
	v_mul_f32_e32 v115, 0xbfb8aa3b, v93
	v_exp_f32_e32 v114, v114
	v_exp_f32_e32 v115, v115
	v_pk_add_f32 v[110:111], v[110:111], 1.0 op_sel_hi:[1,0]
	v_rcp_f32_e32 v131, v44
	v_rcp_f32_e32 v132, v45
	v_pk_add_f32 v[112:113], v[112:113], 1.0 op_sel_hi:[1,0]
	v_rcp_f32_e32 v133, v110
	v_rcp_f32_e32 v134, v111
	v_pk_add_f32 v[114:115], v[114:115], 1.0 op_sel_hi:[1,0]
	v_rcp_f32_e32 v135, v112
	v_rcp_f32_e32 v136, v113
	v_rcp_f32_e32 v137, v114
	v_rcp_f32_e32 v138, v115
	v_mul_f32_e32 v41, v46, v131
	s_mov_b64 vcc, s[2:3]
	v_mul_f32_e32 v44, v47, v132
	s_mov_b64 vcc, s[4:5]
	v_mul_f32_e32 v45, v78, v133
	s_mov_b64 vcc, s[6:7]
	v_bfe_u32 v46, v41, 16, 1
	v_mul_f32_e32 v47, v79, v134
	s_mov_b64 vcc, s[8:9]
	v_bfe_u32 v78, v44, 16, 1
	v_add3_u32 v41, v41, v46, s30
	v_mov_b32_e32 v46, v47
	v_mul_f32_e32 v47, v80, v135
	s_mov_b64 vcc, s[10:11]
	v_add3_u32 v44, v44, v78, s30
	v_mul_f32_e32 v78, v81, v136
	s_mov_b64 vcc, s[12:13]
	v_bfe_u32 v79, v45, 16, 1
	v_bfe_u32 v80, v46, 16, 1
	v_perm_b32 v44, v44, v41, s31
	v_mov_b32_e32 v41, v78
	v_mul_f32_e32 v78, v92, v137
	s_mov_b64 vcc, s[14:15]
	v_add3_u32 v45, v45, v79, s30
	v_bfe_u32 v79, v47, 16, 1
	v_add3_u32 v46, v46, v80, s30
	v_mul_f32_e32 v80, v93, v138
	v_bfe_u32 v81, v41, 16, 1
	v_add3_u32 v47, v47, v79, s30
	v_mov_b32_e32 v79, v80
	v_perm_b32 v45, v46, v45, s31
	v_bfe_u32 v46, v78, 16, 1
	v_add3_u32 v41, v41, v81, s30
	v_bfe_u32 v80, v79, 16, 1
	v_add3_u32 v78, v78, v46, s30
	v_perm_b32 v46, v41, v47, s31
	v_add3_u32 v41, v79, v80, s30
	v_perm_b32 v47, v41, v78, s31
	global_store_dwordx4 v[74:75], v[44:47], off
	v_pk_fma_f32 v[102:103], v[6:7], v[64:65], v[102:103]
	v_pk_fma_f32 v[48:49], v[0:1], v[48:49], v[32:33]
	v_pk_fma_f32 v[64:65], v[2:3], v[64:65], v[34:35]
	v_pk_fma_f32 v[76:77], v[10:11], v[76:77], v[38:39]
	s_waitcnt vmcnt(0)
; DEVINL u16 f2bf(float f) { uint32_t u = __float_as_uint(f); u += 0x7FFFu + ((u >> 16) & 1u); return (u16)(u >> 16); }
; DEVINL float bfs2f(short h) { return __uint_as_float(((uint32_t)(u16)h) << 16); }
; DEVINL void phase_conv(const Params& p, int layer, int wv) {
;     ...
; #pragma unroll 8
;       for (int i = 0; i < 32; ++i) {
;         const bf16x8 r3 = *(const bf16x8*)(src + (size_t)i * HS);
;         bf16x8 o;
; #pragma unroll
;         for (int e = 0; e < 8; ++e) {
;           float v = bias[e] + w[0][e] * bfs2f(r0[e]) + w[1][e] * bfs2f(r1[e]) + w[2][e] * bfs2f(r2[e]) + w[3][e] * bfs2f(r3[e]);
;           v = v / (1.f + __expf(-v));
;           o[e] = (short)f2bf(v);
;         }
;         *(bf16x8*)(xc + (size_t)(tokA + i) * 1536 + ch0) = o;
;         r0 = r1; r1 = r2; r2 = r3;
	v_and_b32_e32 v51, 0xffff0000, v200
	v_lshlrev_b32_e32 v50, 16, v200
	v_and_b32_e32 v75, 0xffff0000, v201
	v_lshlrev_b32_e32 v74, 16, v201
	v_and_b32_e32 v45, 0xffff0000, v202
	v_lshlrev_b32_e32 v44, 16, v202
	v_and_b32_e32 v79, 0xffff0000, v203
	v_lshlrev_b32_e32 v78, 16, v203
	v_pk_fma_f32 v[46:47], v[20:21], v[50:51], v[94:95]
	v_pk_fma_f32 v[80:81], v[22:23], v[74:75], v[96:97]
	v_pk_fma_f32 v[92:93], v[28:29], v[44:45], v[98:99]
	v_pk_fma_f32 v[96:97], v[16:17], v[50:51], v[104:105]
	v_pk_fma_f32 v[98:99], v[18:19], v[74:75], v[102:103]
	v_pk_fma_f32 v[90:91], v[24:25], v[44:45], v[90:91]
	v_pk_fma_f32 v[102:103], v[12:13], v[44:45], v[108:109]
	v_pk_fma_f32 v[104:105], v[8:9], v[44:45], v[36:37]
	v_mul_f32_e32 v41, 0xbfb8aa3b, v46
	v_mul_f32_e32 v45, 0xbfb8aa3b, v47
	v_exp_f32_e32 v44, v41
	v_exp_f32_e32 v45, v45
	v_pk_fma_f32 v[94:95], v[30:31], v[78:79], v[100:101]
	v_pk_fma_f32 v[100:101], v[26:27], v[78:79], v[106:107]
	v_mul_f32_e32 v106, 0xbfb8aa3b, v80
	v_mul_f32_e32 v107, 0xbfb8aa3b, v81
	v_exp_f32_e32 v106, v106
	v_exp_f32_e32 v107, v107
	v_mul_f32_e32 v108, 0xbfb8aa3b, v92
	v_mul_f32_e32 v109, 0xbfb8aa3b, v93
	v_exp_f32_e32 v108, v108
	v_exp_f32_e32 v109, v109
	v_pk_add_f32 v[44:45], v[44:45], 1.0 op_sel_hi:[1,0]
	v_mul_f32_e32 v110, 0xbfb8aa3b, v94
	v_mul_f32_e32 v111, 0xbfb8aa3b, v95
	v_exp_f32_e32 v110, v110
	v_exp_f32_e32 v111, v111
	v_pk_add_f32 v[106:107], v[106:107], 1.0 op_sel_hi:[1,0]
	v_rcp_f32_e32 v127, v44
	v_rcp_f32_e32 v128, v45
	v_pk_add_f32 v[108:109], v[108:109], 1.0 op_sel_hi:[1,0]
	v_rcp_f32_e32 v129, v106
	v_rcp_f32_e32 v130, v107
	v_pk_add_f32 v[110:111], v[110:111], 1.0 op_sel_hi:[1,0]
	v_rcp_f32_e32 v131, v108
	v_rcp_f32_e32 v132, v109
	v_rcp_f32_e32 v133, v110
	v_rcp_f32_e32 v134, v111
	v_mul_f32_e32 v41, v46, v127
	s_mov_b64 vcc, s[2:3]
	v_mul_f32_e32 v44, v47, v128
	s_mov_b64 vcc, s[4:5]
	v_mul_f32_e32 v45, v80, v129
	s_mov_b64 vcc, s[6:7]
	v_bfe_u32 v46, v41, 16, 1
	v_mul_f32_e32 v47, v81, v130
	s_mov_b64 vcc, s[8:9]
	v_bfe_u32 v80, v44, 16, 1
	v_add3_u32 v41, v41, v46, s30
	v_mov_b32_e32 v46, v47
	v_mul_f32_e32 v47, v92, v131
	s_mov_b64 vcc, s[10:11]
	v_add3_u32 v44, v44, v80, s30
	v_mul_f32_e32 v80, v93, v132
	s_mov_b64 vcc, s[12:13]
	v_bfe_u32 v81, v45, 16, 1
	v_bfe_u32 v92, v46, 16, 1
	v_perm_b32 v44, v44, v41, s31
	v_mov_b32_e32 v41, v80
	v_mul_f32_e32 v80, v94, v133
	s_mov_b64 vcc, s[14:15]
	v_add3_u32 v45, v45, v81, s30
	v_bfe_u32 v81, v47, 16, 1
	v_add3_u32 v46, v46, v92, s30
	v_mul_f32_e32 v92, v95, v134
	v_bfe_u32 v93, v41, 16, 1
	v_add3_u32 v47, v47, v81, s30
	v_mov_b32_e32 v81, v92
	v_perm_b32 v45, v46, v45, s31
	v_bfe_u32 v46, v80, 16, 1
	v_add3_u32 v41, v41, v93, s30
	v_bfe_u32 v92, v81, 16, 1
	v_add3_u32 v80, v80, v46, s30
	v_perm_b32 v46, v41, v47, s31
	v_add3_u32 v41, v81, v92, s30
	v_perm_b32 v47, v41, v80, s31
	global_store_dwordx4 v[72:73], v[44:47], off
	v_pk_fma_f32 v[48:49], v[4:5], v[50:51], v[48:49]
	v_pk_fma_f32 v[64:65], v[6:7], v[74:75], v[64:65]
	v_pk_fma_f32 v[76:77], v[14:15], v[78:79], v[76:77]
	v_pk_fma_f32 v[50:51], v[0:1], v[50:51], v[32:33]
	v_pk_fma_f32 v[74:75], v[2:3], v[74:75], v[34:35]
	v_pk_fma_f32 v[78:79], v[10:11], v[78:79], v[38:39]
	s_waitcnt vmcnt(0)
	v_and_b32_e32 v55, 0xffff0000, v204
	v_lshlrev_b32_e32 v54, 16, v204
	v_and_b32_e32 v73, 0xffff0000, v205
	v_lshlrev_b32_e32 v72, 16, v205
	v_and_b32_e32 v45, 0xffff0000, v206
	v_lshlrev_b32_e32 v44, 16, v206
	v_and_b32_e32 v81, 0xffff0000, v207
	v_lshlrev_b32_e32 v80, 16, v207
	v_pk_fma_f32 v[46:47], v[20:21], v[54:55], v[96:97]
	v_pk_fma_f32 v[92:93], v[22:23], v[72:73], v[98:99]
	v_pk_fma_f32 v[90:91], v[28:29], v[44:45], v[90:91]
	v_pk_fma_f32 v[94:95], v[30:31], v[80:81], v[100:101]
	v_pk_fma_f32 v[96:97], v[24:25], v[44:45], v[102:103]
	v_pk_fma_f32 v[98:99], v[12:13], v[44:45], v[104:105]
	v_pk_fma_f32 v[100:101], v[8:9], v[44:45], v[36:37]
	v_mul_f32_e32 v41, 0xbfb8aa3b, v46
	v_mul_f32_e32 v45, 0xbfb8aa3b, v47
	v_exp_f32_e32 v44, v41
	v_exp_f32_e32 v45, v45
	v_mul_f32_e32 v102, 0xbfb8aa3b, v92
	v_mul_f32_e32 v103, 0xbfb8aa3b, v93
	v_exp_f32_e32 v102, v102
	v_exp_f32_e32 v103, v103
	v_mul_f32_e32 v104, 0xbfb8aa3b, v90
	v_mul_f32_e32 v105, 0xbfb8aa3b, v91
	v_exp_f32_e32 v104, v104
	v_exp_f32_e32 v105, v105
	v_pk_add_f32 v[44:45], v[44:45], 1.0 op_sel_hi:[1,0]
	v_mul_f32_e32 v106, 0xbfb8aa3b, v94
	v_mul_f32_e32 v107, 0xbfb8aa3b, v95
	v_exp_f32_e32 v106, v106
	v_exp_f32_e32 v107, v107
	v_pk_add_f32 v[102:103], v[102:103], 1.0 op_sel_hi:[1,0]
	v_rcp_f32_e32 v123, v44
	v_rcp_f32_e32 v124, v45
	v_pk_add_f32 v[104:105], v[104:105], 1.0 op_sel_hi:[1,0]
	v_rcp_f32_e32 v125, v102
	v_rcp_f32_e32 v126, v103
	v_pk_add_f32 v[106:107], v[106:107], 1.0 op_sel_hi:[1,0]
	v_rcp_f32_e32 v127, v104
	v_rcp_f32_e32 v128, v105
	v_rcp_f32_e32 v129, v106
	v_rcp_f32_e32 v130, v107
	v_mul_f32_e32 v41, v46, v123
	s_mov_b64 vcc, s[2:3]
	v_mul_f32_e32 v44, v47, v124
	s_mov_b64 vcc, s[4:5]
	v_mul_f32_e32 v45, v92, v125
	s_mov_b64 vcc, s[6:7]
	v_bfe_u32 v46, v41, 16, 1
	v_mul_f32_e32 v47, v93, v126
	s_mov_b64 vcc, s[8:9]
	v_bfe_u32 v92, v44, 16, 1
	v_add3_u32 v41, v41, v46, s30
	v_mov_b32_e32 v46, v47
	v_mul_f32_e32 v47, v90, v127
	s_mov_b64 vcc, s[10:11]
	v_add3_u32 v44, v44, v92, s30
	v_mul_f32_e32 v90, v91, v128
	s_mov_b64 vcc, s[12:13]
	v_bfe_u32 v92, v46, 16, 1
	v_perm_b32 v44, v44, v41, s31
	v_mov_b32_e32 v41, v90
	v_mul_f32_e32 v90, v94, v129
	s_mov_b64 vcc, s[14:15]
	v_bfe_u32 v93, v45, 16, 1
	v_bfe_u32 v91, v47, 16, 1
	v_add3_u32 v46, v46, v92, s30
	v_mul_f32_e32 v92, v95, v130
	v_add3_u32 v45, v45, v93, s30
	v_bfe_u32 v93, v41, 16, 1
	v_add3_u32 v47, v47, v91, s30
	v_mov_b32_e32 v91, v92
	v_perm_b32 v45, v46, v45, s31
	v_bfe_u32 v46, v90, 16, 1
	v_add3_u32 v41, v41, v93, s30
	v_bfe_u32 v92, v91, 16, 1
	v_add3_u32 v90, v90, v46, s30
	v_perm_b32 v46, v41, v47, s31
	v_add3_u32 v41, v91, v92, s30
	v_perm_b32 v47, v41, v90, s31
	global_store_dwordx4 v[70:71], v[44:47], off
	v_pk_fma_f32 v[48:49], v[16:17], v[54:55], v[48:49]
	v_pk_fma_f32 v[64:65], v[18:19], v[72:73], v[64:65]
	v_pk_fma_f32 v[76:77], v[26:27], v[80:81], v[76:77]
	v_pk_fma_f32 v[50:51], v[4:5], v[54:55], v[50:51]
	v_pk_fma_f32 v[54:55], v[0:1], v[54:55], v[32:33]
	v_pk_fma_f32 v[74:75], v[6:7], v[72:73], v[74:75]
	v_pk_fma_f32 v[72:73], v[2:3], v[72:73], v[34:35]
	v_pk_fma_f32 v[78:79], v[14:15], v[80:81], v[78:79]
	v_pk_fma_f32 v[80:81], v[10:11], v[80:81], v[38:39]
	s_waitcnt vmcnt(0)
; DEVINL u16 f2bf(float f) { uint32_t u = __float_as_uint(f); u += 0x7FFFu + ((u >> 16) & 1u); return (u16)(u >> 16); }
; DEVINL float bfs2f(short h) { return __uint_as_float(((uint32_t)(u16)h) << 16); }
; DEVINL void phase_conv(const Params& p, int layer, int wv) {
;     ...
; #pragma unroll 8
;       for (int i = 0; i < 32; ++i) {
;         const bf16x8 r3 = *(const bf16x8*)(src + (size_t)i * HS);
;         bf16x8 o;
; #pragma unroll
;         for (int e = 0; e < 8; ++e) {
;           float v = bias[e] + w[0][e] * bfs2f(r0[e]) + w[1][e] * bfs2f(r1[e]) + w[2][e] * bfs2f(r2[e]) + w[3][e] * bfs2f(r3[e]);
;           v = v / (1.f + __expf(-v));
;           o[e] = (short)f2bf(v);
;         }
;         *(bf16x8*)(xc + (size_t)(tokA + i) * 1536 + ch0) = o;
;         r0 = r1; r1 = r2; r2 = r3;
	v_and_b32_e32 v71, 0xffff0000, v208
	v_lshlrev_b32_e32 v70, 16, v208
	v_and_b32_e32 v83, 0xffff0000, v209
	v_lshlrev_b32_e32 v82, 16, v209
	v_and_b32_e32 v45, 0xffff0000, v210
	v_lshlrev_b32_e32 v44, 16, v210
	v_and_b32_e32 v91, 0xffff0000, v211
	v_lshlrev_b32_e32 v90, 16, v211
	v_pk_fma_f32 v[46:47], v[20:21], v[70:71], v[48:49]
	v_pk_fma_f32 v[48:49], v[22:23], v[82:83], v[64:65]
	v_pk_fma_f32 v[64:65], v[28:29], v[44:45], v[96:97]
	v_pk_fma_f32 v[92:93], v[24:25], v[44:45], v[98:99]
	v_pk_fma_f32 v[94:95], v[12:13], v[44:45], v[100:101]
	v_pk_fma_f32 v[96:97], v[8:9], v[44:45], v[36:37]
	v_mul_f32_e32 v41, 0xbfb8aa3b, v46
	v_mul_f32_e32 v45, 0xbfb8aa3b, v47
	v_exp_f32_e32 v44, v41
	v_exp_f32_e32 v45, v45
	v_mul_f32_e32 v98, 0xbfb8aa3b, v48
	v_mul_f32_e32 v99, 0xbfb8aa3b, v49
	v_exp_f32_e32 v98, v98
	v_exp_f32_e32 v99, v99
	v_mul_f32_e32 v100, 0xbfb8aa3b, v64
	v_mul_f32_e32 v101, 0xbfb8aa3b, v65
	v_pk_fma_f32 v[76:77], v[30:31], v[90:91], v[76:77]
	v_exp_f32_e32 v100, v100
	v_exp_f32_e32 v101, v101
	v_pk_add_f32 v[44:45], v[44:45], 1.0 op_sel_hi:[1,0]
	v_mul_f32_e32 v102, 0xbfb8aa3b, v76
	v_mul_f32_e32 v103, 0xbfb8aa3b, v77
	v_exp_f32_e32 v102, v102
	v_exp_f32_e32 v103, v103
	v_pk_add_f32 v[98:99], v[98:99], 1.0 op_sel_hi:[1,0]
	v_rcp_f32_e32 v119, v44
	v_rcp_f32_e32 v120, v45
	v_pk_add_f32 v[100:101], v[100:101], 1.0 op_sel_hi:[1,0]
	v_rcp_f32_e32 v121, v98
	v_rcp_f32_e32 v122, v99
	v_pk_add_f32 v[102:103], v[102:103], 1.0 op_sel_hi:[1,0]
	v_rcp_f32_e32 v123, v100
	v_rcp_f32_e32 v124, v101
	v_rcp_f32_e32 v125, v102
	v_rcp_f32_e32 v126, v103
	v_mul_f32_e32 v41, v46, v119
	s_mov_b64 vcc, s[2:3]
	v_mul_f32_e32 v44, v47, v120
	s_mov_b64 vcc, s[4:5]
	v_mul_f32_e32 v45, v48, v121
	s_mov_b64 vcc, s[6:7]
	v_bfe_u32 v46, v41, 16, 1
	v_mul_f32_e32 v47, v49, v122
	s_mov_b64 vcc, s[8:9]
	v_bfe_u32 v48, v44, 16, 1
	v_add3_u32 v41, v41, v46, s30
	v_mov_b32_e32 v46, v47
	v_mul_f32_e32 v47, v64, v123
	s_mov_b64 vcc, s[10:11]
	v_add3_u32 v44, v44, v48, s30
	v_mul_f32_e32 v48, v65, v124
	s_mov_b64 vcc, s[12:13]
	v_bfe_u32 v49, v45, 16, 1
	v_bfe_u32 v64, v46, 16, 1
	v_perm_b32 v44, v44, v41, s31
	v_mov_b32_e32 v41, v48
	v_mul_f32_e32 v48, v76, v125
	s_mov_b64 vcc, s[14:15]
	v_add3_u32 v45, v45, v49, s30
	v_bfe_u32 v49, v47, 16, 1
	v_add3_u32 v46, v46, v64, s30
	v_mul_f32_e32 v64, v77, v126
	v_bfe_u32 v65, v41, 16, 1
	v_add3_u32 v47, v47, v49, s30
	v_mov_b32_e32 v49, v64
	v_perm_b32 v45, v46, v45, s31
	v_bfe_u32 v46, v48, 16, 1
	v_add3_u32 v41, v41, v65, s30
	v_bfe_u32 v64, v49, 16, 1
	v_add3_u32 v48, v48, v46, s30
	v_perm_b32 v46, v41, v47, s31
	v_add3_u32 v41, v49, v64, s30
	v_perm_b32 v47, v41, v48, s31
	global_store_dwordx4 v[68:69], v[44:47], off
	v_pk_fma_f32 v[50:51], v[16:17], v[70:71], v[50:51]
	v_pk_fma_f32 v[54:55], v[4:5], v[70:71], v[54:55]
	v_pk_fma_f32 v[70:71], v[0:1], v[70:71], v[32:33]
	v_pk_fma_f32 v[74:75], v[18:19], v[82:83], v[74:75]
	v_pk_fma_f32 v[72:73], v[6:7], v[82:83], v[72:73]
	v_pk_fma_f32 v[82:83], v[2:3], v[82:83], v[34:35]
	v_pk_fma_f32 v[78:79], v[26:27], v[90:91], v[78:79]
	v_pk_fma_f32 v[80:81], v[14:15], v[90:91], v[80:81]
	v_pk_fma_f32 v[90:91], v[10:11], v[90:91], v[38:39]
	s_waitcnt vmcnt(0)
	v_and_b32_e32 v49, 0xffff0000, v212
	v_lshlrev_b32_e32 v48, 16, v212
	v_pk_fma_f32 v[50:51], v[20:21], v[48:49], v[50:51]
	v_and_b32_e32 v65, 0xffff0000, v213
	v_lshlrev_b32_e32 v64, 16, v213
	v_pk_fma_f32 v[54:55], v[16:17], v[48:49], v[54:55]
	v_pk_fma_f32 v[70:71], v[4:5], v[48:49], v[70:71]
	v_mul_f32_e32 v41, 0xbfb8aa3b, v50
	v_mul_f32_e32 v49, 0xbfb8aa3b, v51
	v_pk_fma_f32 v[74:75], v[22:23], v[64:65], v[74:75]
	v_exp_f32_e32 v48, v41
	v_exp_f32_e32 v49, v49
	v_and_b32_e32 v69, 0xffff0000, v214
	v_lshlrev_b32_e32 v68, 16, v214
	v_pk_fma_f32 v[72:73], v[18:19], v[64:65], v[72:73]
	v_pk_fma_f32 v[64:65], v[6:7], v[64:65], v[82:83]
	v_mul_f32_e32 v82, 0xbfb8aa3b, v74
	v_mul_f32_e32 v83, 0xbfb8aa3b, v75
	v_and_b32_e32 v77, 0xffff0000, v215
	v_lshlrev_b32_e32 v76, 16, v215
	v_pk_fma_f32 v[84:85], v[28:29], v[68:69], v[92:93]
	v_exp_f32_e32 v82, v82
	v_exp_f32_e32 v83, v83
	v_pk_fma_f32 v[78:79], v[30:31], v[76:77], v[78:79]
	v_pk_fma_f32 v[80:81], v[26:27], v[76:77], v[80:81]
	v_pk_fma_f32 v[76:77], v[14:15], v[76:77], v[90:91]
	v_mul_f32_e32 v90, 0xbfb8aa3b, v84
	v_mul_f32_e32 v91, 0xbfb8aa3b, v85
	v_exp_f32_e32 v90, v90
	v_exp_f32_e32 v91, v91
	v_pk_add_f32 v[48:49], v[48:49], 1.0 op_sel_hi:[1,0]
	v_pk_fma_f32 v[92:93], v[24:25], v[68:69], v[94:95]
	v_mul_f32_e32 v94, 0xbfb8aa3b, v78
	v_mul_f32_e32 v95, 0xbfb8aa3b, v79
	v_pk_fma_f32 v[68:69], v[12:13], v[68:69], v[96:97]
	v_exp_f32_e32 v94, v94
	v_exp_f32_e32 v95, v95
	v_pk_add_f32 v[82:83], v[82:83], 1.0 op_sel_hi:[1,0]
	v_rcp_f32_e32 v111, v48
	v_rcp_f32_e32 v112, v49
	v_pk_add_f32 v[90:91], v[90:91], 1.0 op_sel_hi:[1,0]
	v_rcp_f32_e32 v113, v82
	v_rcp_f32_e32 v114, v83
	v_pk_add_f32 v[94:95], v[94:95], 1.0 op_sel_hi:[1,0]
	v_rcp_f32_e32 v115, v90
	v_rcp_f32_e32 v116, v91
	v_rcp_f32_e32 v117, v94
	v_rcp_f32_e32 v118, v95
	v_mul_f32_e32 v41, v50, v111
	s_mov_b64 vcc, s[2:3]
	v_mul_f32_e32 v48, v51, v112
	s_mov_b64 vcc, s[4:5]
	v_mul_f32_e32 v49, v74, v113
	s_mov_b64 vcc, s[6:7]
	v_bfe_u32 v50, v41, 16, 1
	v_mul_f32_e32 v51, v75, v114
	s_mov_b64 vcc, s[8:9]
	v_bfe_u32 v74, v48, 16, 1
	v_add3_u32 v41, v41, v50, s30
	v_mov_b32_e32 v50, v51
	v_mul_f32_e32 v51, v84, v115
	s_mov_b64 vcc, s[10:11]
	v_add3_u32 v48, v48, v74, s30
	v_mul_f32_e32 v74, v85, v116
	s_mov_b64 vcc, s[12:13]
	v_bfe_u32 v75, v49, 16, 1
	v_perm_b32 v48, v48, v41, s31
	v_mov_b32_e32 v41, v74
	v_mul_f32_e32 v74, v78, v117
	s_mov_b64 vcc, s[14:15]
	v_bfe_u32 v82, v50, 16, 1
	v_add3_u32 v49, v49, v75, s30
	v_bfe_u32 v75, v51, 16, 1
	v_mul_f32_e32 v78, v79, v118
	v_add3_u32 v50, v50, v82, s30
	v_bfe_u32 v82, v41, 16, 1
	v_add3_u32 v51, v51, v75, s30
	v_mov_b32_e32 v75, v78
	v_perm_b32 v49, v50, v49, s31
	v_bfe_u32 v50, v74, 16, 1
	v_add3_u32 v41, v41, v82, s30
	v_bfe_u32 v78, v75, 16, 1
	v_add3_u32 v74, v74, v50, s30
	v_perm_b32 v50, v41, v51, s31
	v_add3_u32 v41, v75, v78, s30
	v_perm_b32 v51, v41, v74, s31
	global_store_dwordx4 v[66:67], v[48:51], off
	s_waitcnt vmcnt(0)
; DEVINL u16 f2bf(float f) { uint32_t u = __float_as_uint(f); u += 0x7FFFu + ((u >> 16) & 1u); return (u16)(u >> 16); }
; DEVINL float bfs2f(short h) { return __uint_as_float(((uint32_t)(u16)h) << 16); }
; DEVINL void phase_conv(const Params& p, int layer, int wv) {
;     ...
;     for (int run = blockIdx.x * 2 + half; run < T_TOK / 32; run += gridDim.x * 2) {
;     ...
; #pragma unroll 8
;       for (int i = 0; i < 32; ++i) {
;         const bf16x8 r3 = *(const bf16x8*)(src + (size_t)i * HS);
;         bf16x8 o;
; #pragma unroll
;         for (int e = 0; e < 8; ++e) {
;           float v = bias[e] + w[0][e] * bfs2f(r0[e]) + w[1][e] * bfs2f(r1[e]) + w[2][e] * bfs2f(r2[e]) + w[3][e] * bfs2f(r3[e]);
;           v = v / (1.f + __expf(-v));
;           o[e] = (short)f2bf(v);
;         }
;         *(bf16x8*)(xc + (size_t)(tokA + i) * 1536 + ch0) = o;
;         r0 = r1; r1 = r2; r2 = r3;
;       }
	v_and_b32_e32 v67, 0xffff0000, v216
	v_lshlrev_b32_e32 v66, 16, v216
	v_and_b32_e32 v75, 0xffff0000, v217
	v_lshlrev_b32_e32 v74, 16, v217
	v_pk_fma_f32 v[54:55], v[20:21], v[66:67], v[54:55]
	v_pk_fma_f32 v[72:73], v[22:23], v[74:75], v[72:73]
	v_pk_fma_f32 v[74:75], v[18:19], v[74:75], v[64:65]
	v_mul_f32_e32 v41, 0xbfb8aa3b, v54
	v_mul_f32_e32 v65, 0xbfb8aa3b, v55
	v_exp_f32_e32 v64, v41
	v_exp_f32_e32 v65, v65
	v_and_b32_e32 v79, 0xffff0000, v218
	v_lshlrev_b32_e32 v78, 16, v218
	v_pk_fma_f32 v[70:71], v[16:17], v[66:67], v[70:71]
	v_mul_f32_e32 v66, 0xbfb8aa3b, v72
	v_mul_f32_e32 v67, 0xbfb8aa3b, v73
	v_pk_fma_f32 v[84:85], v[28:29], v[78:79], v[92:93]
	v_exp_f32_e32 v66, v66
	v_exp_f32_e32 v67, v67
	v_and_b32_e32 v83, 0xffff0000, v219
	v_lshlrev_b32_e32 v82, 16, v219
	v_pk_fma_f32 v[68:69], v[24:25], v[78:79], v[68:69]
	v_mul_f32_e32 v78, 0xbfb8aa3b, v84
	v_mul_f32_e32 v79, 0xbfb8aa3b, v85
	v_pk_fma_f32 v[80:81], v[30:31], v[82:83], v[80:81]
	v_exp_f32_e32 v78, v78
	v_exp_f32_e32 v79, v79
	v_pk_add_f32 v[64:65], v[64:65], 1.0 op_sel_hi:[1,0]
	v_pk_fma_f32 v[76:77], v[26:27], v[82:83], v[76:77]
	v_mul_f32_e32 v82, 0xbfb8aa3b, v80
	v_mul_f32_e32 v83, 0xbfb8aa3b, v81
	v_exp_f32_e32 v82, v82
	v_exp_f32_e32 v83, v83
	v_pk_add_f32 v[66:67], v[66:67], 1.0 op_sel_hi:[1,0]
	v_rcp_f32_e32 v103, v64
	v_rcp_f32_e32 v104, v65
	v_pk_add_f32 v[78:79], v[78:79], 1.0 op_sel_hi:[1,0]
	v_rcp_f32_e32 v105, v66
	v_rcp_f32_e32 v106, v67
	v_pk_add_f32 v[82:83], v[82:83], 1.0 op_sel_hi:[1,0]
	v_rcp_f32_e32 v107, v78
	v_rcp_f32_e32 v108, v79
	v_rcp_f32_e32 v109, v82
	v_rcp_f32_e32 v110, v83
	v_mul_f32_e32 v41, v54, v103
	s_mov_b64 vcc, s[2:3]
	v_mul_f32_e32 v54, v55, v104
	s_mov_b64 vcc, s[4:5]
	v_mul_f32_e32 v55, v72, v105
	s_mov_b64 vcc, s[6:7]
	v_bfe_u32 v64, v41, 16, 1
	v_mul_f32_e32 v65, v73, v106
	s_mov_b64 vcc, s[8:9]
	v_bfe_u32 v66, v54, 16, 1
	v_add3_u32 v41, v41, v64, s30
	v_mul_f32_e32 v64, v84, v107
	s_mov_b64 vcc, s[10:11]
	v_add3_u32 v54, v54, v66, s30
	v_mul_f32_e32 v72, v85, v108
	s_mov_b64 vcc, s[12:13]
	v_bfe_u32 v67, v55, 16, 1
	v_mov_b32_e32 v66, v64
	v_bfe_u32 v73, v65, 16, 1
	v_perm_b32 v64, v54, v41, s31
	v_mul_f32_e32 v54, v80, v109
	s_mov_b64 vcc, s[14:15]
	v_add3_u32 v55, v55, v67, s30
	v_mov_b32_e32 v41, v72
	v_add3_u32 v65, v65, v73, s30
	v_mul_f32_e32 v72, v81, v110
	v_bfe_u32 v67, v66, 16, 1
	v_bfe_u32 v73, v41, 16, 1
	v_perm_b32 v65, v65, v55, s31
	v_mov_b32_e32 v55, v72
	v_add3_u32 v66, v66, v67, s30
	v_bfe_u32 v67, v54, 16, 1
	v_add3_u32 v41, v41, v73, s30
	v_bfe_u32 v72, v55, 16, 1
	v_add3_u32 v54, v54, v67, s30
	v_perm_b32 v66, v41, v66, s31
	v_add3_u32 v41, v55, v72, s30
	v_perm_b32 v67, v41, v54, s31
	global_store_dwordx4 v[52:53], v[64:67], off
	v_lshl_add_u64 v[42:43], v[42:43], 0, s[22:23]
	s_waitcnt vmcnt(0)
	v_and_b32_e32 v65, 0xffff0000, v220
	v_lshlrev_b32_e32 v64, 16, v220
	v_and_b32_e32 v73, 0xffff0000, v222
	v_lshlrev_b32_e32 v72, 16, v222
	v_pk_fma_f32 v[64:65], v[20:21], v[64:65], v[70:71]
	v_and_b32_e32 v67, 0xffff0000, v221
	v_lshlrev_b32_e32 v66, 16, v221
	v_pk_fma_f32 v[68:69], v[28:29], v[72:73], v[68:69]
	v_mul_f32_e32 v41, 0xbfb8aa3b, v64
	v_mul_f32_e32 v73, 0xbfb8aa3b, v65
	v_pk_fma_f32 v[66:67], v[22:23], v[66:67], v[74:75]
	v_exp_f32_e32 v72, v41
	v_exp_f32_e32 v73, v73
	v_mul_f32_e32 v74, 0xbfb8aa3b, v66
	v_mul_f32_e32 v75, 0xbfb8aa3b, v67
	v_and_b32_e32 v79, 0xffff0000, v223
	v_lshlrev_b32_e32 v78, 16, v223
	v_exp_f32_e32 v74, v74
	v_exp_f32_e32 v75, v75
	v_pk_fma_f32 v[70:71], v[30:31], v[78:79], v[76:77]
	v_mul_f32_e32 v76, 0xbfb8aa3b, v68
	v_mul_f32_e32 v77, 0xbfb8aa3b, v69
	v_exp_f32_e32 v76, v76
	v_exp_f32_e32 v77, v77
	v_pk_add_f32 v[72:73], v[72:73], 1.0 op_sel_hi:[1,0]
	v_mul_f32_e32 v78, 0xbfb8aa3b, v70
	v_mul_f32_e32 v79, 0xbfb8aa3b, v71
	v_exp_f32_e32 v78, v78
	v_exp_f32_e32 v79, v79
	v_pk_add_f32 v[74:75], v[74:75], 1.0 op_sel_hi:[1,0]
	v_rcp_f32_e32 v97, v72
	v_rcp_f32_e32 v98, v73
	v_pk_add_f32 v[76:77], v[76:77], 1.0 op_sel_hi:[1,0]
	v_rcp_f32_e32 v99, v74
	v_rcp_f32_e32 v100, v75
	v_pk_add_f32 v[78:79], v[78:79], 1.0 op_sel_hi:[1,0]
	v_rcp_f32_e32 v101, v76
	v_rcp_f32_e32 v102, v77
	v_rcp_f32_e32 v103, v78
	v_rcp_f32_e32 v104, v79
	v_mul_f32_e32 v41, v64, v97
	s_mov_b64 vcc, s[2:3]
	v_mul_f32_e32 v64, v65, v98
	s_mov_b64 vcc, s[4:5]
	v_mul_f32_e32 v65, v66, v99
	s_mov_b64 vcc, s[6:7]
	v_mul_f32_e32 v66, v67, v100
	s_mov_b64 vcc, s[8:9]
	v_bfe_u32 v72, v41, 16, 1
	v_bfe_u32 v73, v64, 16, 1
	v_mul_f32_e32 v67, v68, v101
	s_mov_b64 vcc, s[10:11]
	v_add3_u32 v41, v41, v72, s30
	v_add3_u32 v64, v64, v73, s30
	v_mul_f32_e32 v68, v69, v102
	s_mov_b64 vcc, s[12:13]
	v_perm_b32 v64, v64, v41, s31
	v_mov_b32_e32 v41, v68
	v_mul_f32_e32 v68, v70, v103
	s_mov_b64 vcc, s[14:15]
	v_bfe_u32 v72, v65, 16, 1
	v_bfe_u32 v73, v66, 16, 1
	v_bfe_u32 v69, v67, 16, 1
	v_mul_f32_e32 v70, v71, v104
	v_add3_u32 v65, v65, v72, s30
	v_add3_u32 v66, v66, v73, s30
	v_bfe_u32 v72, v41, 16, 1
	v_add3_u32 v67, v67, v69, s30
	v_mov_b32_e32 v69, v70
	v_perm_b32 v65, v66, v65, s31
	v_bfe_u32 v66, v68, 16, 1
	v_add3_u32 v41, v41, v72, s30
	v_bfe_u32 v70, v69, 16, 1
	v_add3_u32 v68, v68, v66, s30
	v_perm_b32 v66, v41, v67, s31
	v_add3_u32 v41, v69, v70, s30
	v_perm_b32 v67, v41, v68, s31
	global_store_dwordx4 v[62:63], v[64:67], off
	s_cbranch_scc0 .LBB0_1477
	v_add_u32_e32 v88, s24, v88
	v_cmp_lt_i32_e32 vcc, s37, v88
	s_or_b64 s[18:19], vcc, s[18:19]
	v_add_u32_e32 v89, s25, v89
	s_andn2_b64 exec, exec, s[18:19]
	s_cbranch_execnz .LBB0_1470
